# softmax row-max across lane groups via v_permlane16/32_swap instead of LDS bpermute round trips; ws pointer from spill lanes in barrier
# speedup vs baseline: 1.0038x; 1.0038x over previous
.LBB0_314:
	s_mov_b32 s0, s91
	s_mov_b32 s64, 0
	s_waitcnt vmcnt(0)
	s_waitcnt vmcnt(0) lgkmcnt(0)
	v_or_b32_e32 v0, s0, v230
	v_cmp_eq_u32_e32 vcc, 0, v0
	s_barrier
	s_and_saveexec_b64 s[0:1], vcc
	s_cbranch_execz .LBB0_358
	v_writelane_b32 v2, s4, 1
	v_writelane_b32 v2, s5, 2
	v_writelane_b32 v2, s6, 3
	v_writelane_b32 v2, s7, 4
	v_readlane_b32 s4, v254, 45
	v_readlane_b32 s5, v254, 46
	s_getreg_b32 s6, hwreg(HW_REG_XCC_ID, 0, 4)
	s_nop 0
	v_mov_b32_e32 v0, 0x20010
	ds_read_b32 v3, v0
	ds_read_b32 v4, v0 offset:4
	ds_read_b32 v5, v0 offset:8
	s_and_b32 s6, s6, 15
	s_lshl_b32 s6, s6, 8
	v_mov_b32_e32 v13, 0x3400
	v_mov_b32_e32 v8, 1
	v_mov_b32_e32 v14, 0
	s_waitcnt lgkmcnt(0)
	s_add_u32 s4, s4, 0xee42000
	s_addc_u32 s5, s5, 0
	v_mov_b32_e32 v6, s6
	v_add_u32_e32 v7, 0x400, v6
	v_add_u32_e32 v6, 0x1400, v6
	buffer_inv sc1
	global_atomic_add v9, v6, v8, s[4:5] sc0
	v_add_u32_e32 v10, 1, v5
	v_mul_lo_u32 v11, v10, v3
	v_mul_lo_u32 v12, v10, v4
	s_waitcnt vmcnt(0)
	v_add_u32_e32 v9, 1, v9
	v_cmp_eq_u32_e32 vcc, v9, v11
	s_cbranch_vccz .Lhb_poll_3
	buffer_wbl2 sc1
	s_waitcnt vmcnt(0)
	global_atomic_add v13, v8, s[4:5]

.LBB0_408:
	s_andn2_b64 vcc, exec, s[0:1]
	s_cbranch_vccnz .LBB0_416
	s_add_i32 s0, s28, 0xfffffd00
	s_lshr_b32 s4, s0, 4
	s_bfe_u32 s5, s28, 0x10003
	s_mov_b32 s64, 0
	s_xor_b64 s[0:1], s[64:65], s[62:63]
	s_add_u32 s0, s0, 0x823e000
	s_mov_b32 s2, s91
	s_addc_u32 s1, s1, 0
	s_lshl_b32 s3, s28, 5
	v_or_b32_e32 v58, s2, v230
	s_lshl_b32 s2, s4, 8
	s_and_b32 s3, s3, 0xe0
	v_ashrrev_i32_e32 v2, 4, v58
	v_and_b32_e32 v2, -16, v2
	s_or_b32 s2, s2, s3
	v_add_u32_e32 v59, s2, v2
	v_mov_b64_e32 v[2:3], s[0:1]
	v_mad_i64_i32 v[2:3], s[2:3], v59, s66, v[2:3]
	s_mul_i32 s64, s4, 0xf0000
	v_lshrrev_b32_e32 v0, 6, v58
	s_lshl_b32 s6, s5, 2
	s_lshl_b64 s[2:3], s[64:65], 1
	v_and_or_b32 v60, v0, 3, s6
	s_add_u32 s0, s0, s2
	s_mov_b32 s2, 0
	v_lshlrev_b32_e32 v0, 7, v60
	s_mov_b32 s2, 0
	v_readlane_b32 s8, v251, 62
	v_readlane_b32 s2, v254, 62
	v_lshl_add_u64 v[2:3], v[2:3], 0, v[0:1]
	v_readlane_b32 s14, v252, 4
	v_or_b32_e32 v0, s2, v60
	v_readlane_b32 s15, v252, 5
	s_mov_b32 s6, s91
	s_addc_u32 s1, s1, s3
	v_lshl_add_u64 v[4:5], v[0:1], 2, s[14:15]
	global_load_dword v26, v[4:5], off
	s_lshl_b32 s2, s5, 7
	v_bitop3_b32 v33, s6, 15, v230 bitop3:0xc8
	v_or_b32_e32 v32, s6, v230
	v_mul_u32_u24_e32 v0, 0xf00, v33
	v_bfe_u32 v62, v32, 4, 2
	v_lshlrev_b32_e32 v0, 1, v0
	v_lshl_add_u64 v[2:3], v[2:3], 0, v[0:1]
	v_lshlrev_b32_e32 v0, 4, v62
	v_add_u32_e32 v10, 0x200, v32
	v_lshl_add_u64 v[2:3], v[2:3], 0, v[0:1]
	v_ashrrev_i32_e32 v0, 31, v32
	v_ashrrev_i32_e32 v11, 31, v10
	v_lshrrev_b32_e32 v0, 29, v0
	v_lshrrev_b32_e32 v11, 29, v11
	v_add_u32_e32 v0, v32, v0
	v_add_u32_e32 v11, v10, v11
	s_add_u32 s0, s0, s2
	v_ashrrev_i32_e32 v35, 3, v0
	v_and_b32_e32 v0, -8, v0
	v_ashrrev_i32_e32 v36, 3, v11
	v_and_b32_e32 v11, -8, v11
	s_addc_u32 s1, s1, 0
	v_sub_u32_e32 v0, v32, v0
	v_sub_u32_e32 v37, v10, v11
	s_add_u32 s2, s0, 0x1000
	s_waitcnt vmcnt(0)
	v_lshlrev_b32_e32 v14, 3, v0
	v_lshlrev_b32_e32 v10, 3, v37
	s_addc_u32 s3, s1, 0
	v_ashrrev_i32_e32 v15, 31, v14
	v_ashrrev_i32_e32 v11, 31, v10
	s_add_u32 s4, s0, 0x1100
	v_mov_b64_e32 v[22:23], s[2:3]
	s_addc_u32 s5, s1, 0
	v_lshlrev_b64 v[28:29], 1, v[10:11]
	v_lshlrev_b64 v[30:31], 1, v[14:15]
	v_mad_i64_i32 v[18:19], s[2:3], v36, s66, v[22:23]
	v_mad_i64_i32 v[22:23], s[2:3], v35, s66, v[22:23]
	v_mov_b64_e32 v[16:17], s[4:5]
	v_lshl_add_u64 v[18:19], v[18:19], 0, v[28:29]
	v_lshl_add_u64 v[22:23], v[22:23], 0, v[30:31]
	flat_load_dwordx4 v[6:9], v[2:3] offset:3072
	s_nop 0
	flat_load_dwordx4 v[2:5], v[2:3] offset:3136
	v_mad_i64_i32 v[12:13], s[4:5], v36, s66, v[16:17]
	v_mad_i64_i32 v[16:17], s[4:5], v35, s66, v[16:17]
	flat_load_dwordx4 v[18:21], v[18:19]
	v_lshl_add_u64 v[10:11], v[12:13], 0, v[28:29]
	flat_load_dwordx4 v[22:25], v[22:23]
	v_lshl_add_u64 v[14:15], v[16:17], 0, v[30:31]
	flat_load_dwordx4 v[10:13], v[10:11]
	v_bfe_u32 v39, v32, 2, 2
	flat_load_dwordx4 v[14:17], v[14:15]
	v_lshrrev_b32_e32 v34, 4, v32
	v_lshl_or_b32 v39, v62, 2, v39
	v_lshlrev_b32_e32 v32, 3, v32
	v_and_b32_e32 v32, 24, v32
	v_lshlrev_b32_e32 v40, 4, v39
	v_and_b32_e32 v40, 0x60, v40
	v_or_b32_e32 v41, 0x60, v32
	v_xad_u32 v41, v40, v41, 0
	v_lshlrev_b32_e32 v39, 7, v39
	v_add_u32_e32 v61, v41, v39
	v_lshlrev_b32_e32 v41, 7, v35
	v_and_b32_e32 v42, 0xffffe000, v41
	v_add_u32_e32 v42, 0, v42
	v_bitop3_b32 v43, v35, v0, 7 bitop3:0x6c
	v_and_b32_e32 v41, 0x1f80, v41
	v_lshl_add_u32 v43, v43, 4, v42
	v_add_u32_e32 v85, v43, v41
	v_lshlrev_b32_e32 v43, 7, v36
	v_bitop3_b32 v0, v35, v0, 6 bitop3:0x6c
	v_and_b32_e32 v44, 0xffffe000, v43
	v_lshl_add_u32 v0, v0, 4, v42
	v_add_u32_e32 v44, 0, v44
	v_bitop3_b32 v45, v36, v37, 7 bitop3:0x6c
	v_add_u32_e32 v87, v0, v41
	v_bitop3_b32 v0, v36, v37, 6 bitop3:0x6c
	s_add_u32 s2, s0, 0xf1100
	v_and_b32_e32 v43, 0x1f80, v43
	v_lshl_add_u32 v45, v45, 4, v44
	v_lshl_add_u32 v0, v0, 4, v44
	s_addc_u32 s3, s1, 0
	v_bitop3_b32 v38, s6, 7, v230 bitop3:0xc8
	v_add_u32_e32 v86, v45, v43
	v_add_u32_e32 v88, v0, v43
	s_waitcnt lgkmcnt(0)
	s_barrier
	s_waitcnt vmcnt(0)
	ds_write_b128 v85, v[22:25]
	ds_write_b128 v86, v[18:21]
	ds_write_b128 v87, v[14:17] offset:32768
	ds_write_b128 v88, v[10:13] offset:32768
	v_mov_b64_e32 v[10:11], s[2:3]
	s_add_u32 s0, s0, 0xf1000
	v_bitop3_b32 v0, v34, v38, 3 bitop3:0x6c
	v_mad_i64_i32 v[12:13], s[2:3], v36, s66, v[10:11]
	v_mad_i64_i32 v[10:11], s[2:3], v35, s66, v[10:11]
	s_addc_u32 s1, s1, 0
	v_lshl_add_u32 v33, v33, 7, 0
	v_lshlrev_b32_e32 v0, 4, v0
	v_lshl_add_u64 v[18:19], v[10:11], 0, v[30:31]
	v_mov_b64_e32 v[10:11], s[0:1]
	v_add_u32_e32 v67, v33, v0
	v_bitop3_b32 v0, v62, v38, 4 bitop3:0x36
	v_lshl_add_u64 v[22:23], v[12:13], 0, v[28:29]
	v_mad_i64_i32 v[12:13], s[0:1], v36, s66, v[10:11]
	v_mad_i64_i32 v[10:11], s[0:1], v35, s66, v[10:11]
	v_lshlrev_b32_e32 v0, 4, v0
	v_lshl_add_u64 v[14:15], v[12:13], 0, v[28:29]
	v_lshl_add_u64 v[10:11], v[10:11], 0, v[30:31]
	v_add_u32_e32 v66, v33, v0
	v_or_b32_e32 v0, v40, v32
	s_waitcnt lgkmcnt(0)
	s_barrier
	flat_load_dwordx4 v[10:13], v[10:11]
	s_nop 0
	flat_load_dwordx4 v[14:17], v[14:15]
	s_nop 0
	flat_load_dwordx4 v[18:21], v[18:19]
	s_nop 0
	flat_load_dwordx4 v[22:25], v[22:23]
	ds_read_b128 v[28:31], v67
	v_add_u32_e32 v0, 0, v0
	v_add_u32_e32 v65, v0, v39
	v_or_b32_e32 v0, 32, v32
	v_xad_u32 v0, v40, v0, 0
	v_add_u32_e32 v64, v0, v39
	v_or_b32_e32 v0, 64, v32
	ds_read_b128 v[32:35], v66
	s_waitcnt lgkmcnt(0)
	v_mfma_f32_16x16x32_bf16 v[28:31], v[28:31], v[6:9], 0
	v_xad_u32 v0, v40, v0, 0
	v_add_u32_e32 v63, v0, v39
	ds_read_b128 v[36:39], v66 offset:2048
	v_mfma_f32_16x16x32_bf16 v[28:31], v[32:35], v[2:5], v[28:31]
	ds_read_b128 v[32:35], v67 offset:2048
	ds_read_b128 v[40:43], v66 offset:4096
	ds_read_b128 v[44:47], v66 offset:6144
	s_waitcnt lgkmcnt(0)
	v_mfma_f32_16x16x32_bf16 v[32:35], v[32:35], v[6:9], 0
	s_nop 2
	v_max_f32_e32 v0, v29, v29
	v_mul_f32_e32 v27, 0x3fb8aa3b, v26
	v_readlane_b32 s9, v251, 63
	v_mfma_f32_16x16x32_bf16 v[32:35], v[36:39], v[2:5], v[32:35]
	ds_read_b128 v[36:39], v67 offset:4096
	v_readlane_b32 s10, v252, 0
	v_readlane_b32 s11, v252, 1
	s_waitcnt lgkmcnt(0)
	v_mfma_f32_16x16x32_bf16 v[36:39], v[36:39], v[6:9], 0
	v_readlane_b32 s12, v252, 2
	v_readlane_b32 s13, v252, 3
	v_readlane_b32 s16, v252, 6
	v_mfma_f32_16x16x32_bf16 v[36:39], v[40:43], v[2:5], v[36:39]
	ds_read_b128 v[40:43], v67 offset:6144
	v_readlane_b32 s17, v252, 7
	v_readlane_b32 s18, v252, 8
	s_waitcnt lgkmcnt(0)
	v_mfma_f32_16x16x32_bf16 v[40:43], v[40:43], v[6:9], 0
	v_readlane_b32 s19, v252, 9
	v_readlane_b32 s20, v252, 10
	v_readlane_b32 s21, v252, 11
	v_mfma_f32_16x16x32_bf16 v[40:43], v[44:47], v[2:5], v[40:43]
	v_max_f32_e32 v44, v28, v28
	v_max_f32_e32 v0, v44, v0
	v_max3_f32 v0, v0, v30, v31
	v_max3_f32 v0, v0, v32, v33
	v_max3_f32 v0, v0, v34, v35
	v_max3_f32 v0, v0, v36, v37
	v_max3_f32 v0, v0, v38, v39
	s_nop 0
	v_max3_f32 v0, v0, v40, v41
	v_max3_f32 v0, v0, v42, v43
	ds_bpermute_b32 v44, v236, v0
	v_readlane_b32 s22, v252, 12
	v_readlane_b32 s23, v252, 13
	s_waitcnt lgkmcnt(0)
	v_max_f32_e32 v44, v44, v44
	v_max_f32_e32 v0, v0, v44
	ds_bpermute_b32 v44, v231, v0
	s_waitcnt lgkmcnt(0)
	v_max_f32_e32 v44, v44, v44
	v_max_f32_e32 v0, v0, v44
	v_mul_f32_e32 v0, 0x3fb8aa3b, v0
	v_max_f32_e32 v0, v27, v0
	v_fma_f32 v27, v28, s33, -v0
	v_exp_f32_e32 v68, v27
	v_fma_f32 v27, v29, s33, -v0
	v_exp_f32_e32 v69, v27
	v_fma_f32 v27, v30, s33, -v0
	v_exp_f32_e32 v70, v27
	v_fma_f32 v27, v31, s33, -v0
	v_exp_f32_e32 v71, v27
	v_fma_f32 v27, v32, s33, -v0
	v_exp_f32_e32 v72, v27
	v_fma_f32 v27, v33, s33, -v0
	v_exp_f32_e32 v73, v27
	v_fma_f32 v27, v34, s33, -v0
	v_fma_f32 v26, v26, s33, -v0
	v_exp_f32_e32 v74, v27
	v_fma_f32 v27, v35, s33, -v0
	v_exp_f32_e32 v75, v27
	v_fma_f32 v27, v36, s33, -v0
	v_exp_f32_e32 v84, v26
	v_exp_f32_e32 v76, v27
	v_fma_f32 v27, v37, s33, -v0
	v_exp_f32_e32 v77, v27
	v_fma_f32 v27, v38, s33, -v0
	v_exp_f32_e32 v78, v27
	v_fma_f32 v27, v39, s33, -v0
	v_exp_f32_e32 v79, v27
	v_fma_f32 v27, v40, s33, -v0
	v_cmp_neq_f32_e32 vcc, 1.0, v84
	ds_read_b64_tr_b16 v[30:31], v65 offset:32768
	ds_read_b64_tr_b16 v[32:33], v65 offset:34816
	v_exp_f32_e32 v80, v27
	v_fma_f32 v27, v41, s33, -v0
	s_cmp_lg_u64 vcc, 0
	v_exp_f32_e32 v81, v27
	v_fma_f32 v27, v42, s33, -v0
	v_mul_f32_e32 v26, 0, v84
	s_cselect_b64 vcc, -1, 0
	v_exp_f32_e32 v82, v27
	v_fma_f32 v27, v43, s33, -v0
	v_cndmask_b32_e32 v26, 0, v26, vcc
	v_exp_f32_e32 v83, v27
	v_mov_b32_e32 v27, v26
	v_mov_b32_e32 v28, v26
	v_mov_b32_e32 v29, v26
	v_cvt_pk_bf16_f32 v42, v68, v69
	v_cvt_pk_bf16_f32 v43, v70, v71
	v_cvt_pk_bf16_f32 v44, v72, v73
	v_cvt_pk_bf16_f32 v45, v74, v75
	ds_read_b64_tr_b16 v[34:35], v65 offset:36864
	ds_read_b64_tr_b16 v[36:37], v65 offset:38912
	s_waitcnt lgkmcnt(0)
	v_mfma_f32_16x16x32_bf16 v[30:33], v[30:33], v[42:45], v[26:29]
	v_cvt_pk_bf16_f32 v46, v76, v77
	v_cvt_pk_bf16_f32 v47, v78, v79
	v_cvt_pk_bf16_f32 v48, v80, v81
	v_cvt_pk_bf16_f32 v49, v82, v83
	s_nop 1
	v_mfma_f32_16x16x32_bf16 v[38:41], v[34:37], v[46:49], v[30:33]
	s_nop 2
	ds_read_b64_tr_b16 v[30:31], v64 offset:32768
	ds_read_b64_tr_b16 v[32:33], v64 offset:34816
	ds_read_b64_tr_b16 v[34:35], v64 offset:36864
	ds_read_b64_tr_b16 v[36:37], v64 offset:38912
	s_waitcnt lgkmcnt(0)
	v_mfma_f32_16x16x32_bf16 v[30:33], v[30:33], v[42:45], v[26:29]
	v_mfma_f32_16x16x32_bf16 v[30:33], v[34:37], v[46:49], v[30:33]
	ds_read_b64_tr_b16 v[34:35], v63 offset:32768
	ds_read_b64_tr_b16 v[36:37], v63 offset:34816
	ds_read_b64_tr_b16 v[50:51], v63 offset:36864
	ds_read_b64_tr_b16 v[52:53], v63 offset:38912
	s_waitcnt lgkmcnt(0)
	v_mfma_f32_16x16x32_bf16 v[34:37], v[34:37], v[42:45], v[26:29]
	v_mfma_f32_16x16x32_bf16 v[34:37], v[50:53], v[46:49], v[34:37]
	ds_read_b64_tr_b16 v[50:51], v61 offset:32768
	ds_read_b64_tr_b16 v[52:53], v61 offset:34816
	s_waitcnt lgkmcnt(0)
	v_mfma_f32_16x16x32_bf16 v[26:29], v[50:53], v[42:45], v[26:29]
	ds_read_b64_tr_b16 v[42:43], v61 offset:36864
	ds_read_b64_tr_b16 v[44:45], v61 offset:38912
	ds_read_b128 v[50:53], v66 offset:10240
	ds_read_b128 v[54:57], v66 offset:12288
	ds_read_b128 v[90:93], v66 offset:14336
	s_waitcnt lgkmcnt(0)
	v_mfma_f32_16x16x32_bf16 v[26:29], v[42:45], v[46:49], v[26:29]
	ds_read_b128 v[42:45], v67 offset:8192
	ds_read_b128 v[46:49], v66 offset:8192
	s_waitcnt lgkmcnt(0)
	v_mfma_f32_16x16x32_bf16 v[42:45], v[42:45], v[6:9], 0
	v_mfma_f32_16x16x32_bf16 v[42:45], v[46:49], v[2:5], v[42:45]
	ds_read_b128 v[46:49], v67 offset:10240
	s_waitcnt lgkmcnt(0)
	v_mfma_f32_16x16x32_bf16 v[46:49], v[46:49], v[6:9], 0
	s_nop 4
	v_max_f32_e32 v89, v43, v43
	v_mfma_f32_16x16x32_bf16 v[46:49], v[50:53], v[2:5], v[46:49]
	ds_read_b128 v[50:53], v67 offset:12288
	s_waitcnt lgkmcnt(0)
	v_mfma_f32_16x16x32_bf16 v[50:53], v[50:53], v[6:9], 0
	v_mfma_f32_16x16x32_bf16 v[50:53], v[54:57], v[2:5], v[50:53]
	ds_read_b128 v[54:57], v67 offset:14336
	s_waitcnt lgkmcnt(0)
	v_mfma_f32_16x16x32_bf16 v[54:57], v[54:57], v[6:9], 0
	v_mfma_f32_16x16x32_bf16 v[54:57], v[90:93], v[2:5], v[54:57]
	v_max_f32_e32 v90, v42, v42
	v_max_f32_e32 v89, v90, v89
	v_max3_f32 v89, v89, v44, v45
	v_max3_f32 v89, v89, v46, v47
	v_max3_f32 v89, v89, v48, v49
	v_max3_f32 v89, v89, v50, v51
	v_max3_f32 v89, v89, v52, v53
	s_nop 0
	v_max3_f32 v89, v89, v54, v55
	v_max3_f32 v89, v89, v56, v57
	v_mov_b32_e32 v90, v89
	s_waitcnt lgkmcnt(0)
	s_nop 0
	v_permlane16_swap_b32_e32 v89, v90
	v_max_f32_e32 v89, v89, v90
	v_mov_b32_e32 v90, v89
	s_nop 1
	v_permlane32_swap_b32_e32 v89, v90
	v_max_f32_e32 v89, v89, v90
	v_mul_f32_e32 v89, 0x3fb8aa3b, v89
	v_max_f32_e32 v94, v0, v89
	v_sub_f32_e32 v0, v0, v94
	v_exp_f32_e32 v0, v0
	s_nop 0
	v_cmp_neq_f32_e32 vcc, 1.0, v0
	s_cbranch_vccz .LBB0_411
	v_pk_mul_f32 v[40:41], v[40:41], v[0:1] op_sel_hi:[1,0]
	v_pk_mul_f32 v[38:39], v[38:39], v[0:1] op_sel_hi:[1,0]
	v_pk_mul_f32 v[32:33], v[32:33], v[0:1] op_sel_hi:[1,0]
	v_pk_mul_f32 v[30:31], v[30:31], v[0:1] op_sel_hi:[1,0]
	v_pk_mul_f32 v[36:37], v[36:37], v[0:1] op_sel_hi:[1,0]
	v_pk_mul_f32 v[34:35], v[34:35], v[0:1] op_sel_hi:[1,0]
	v_pk_mul_f32 v[28:29], v[28:29], v[0:1] op_sel_hi:[1,0]
	v_pk_mul_f32 v[26:27], v[26:27], v[0:1] op_sel_hi:[1,0]
.LBB0_411:
	v_fma_f32 v42, v42, s33, -v94
	v_exp_f32_e32 v89, v42
	v_fma_f32 v42, v43, s33, -v94
	v_exp_f32_e32 v90, v42
	v_fma_f32 v42, v44, s33, -v94
	v_exp_f32_e32 v91, v42
	v_fma_f32 v42, v45, s33, -v94
	v_exp_f32_e32 v92, v42
	v_fma_f32 v42, v46, s33, -v94
	v_exp_f32_e32 v93, v42
	v_fma_f32 v42, v47, s33, -v94
	v_exp_f32_e32 v47, v42
	v_fma_f32 v42, v48, s33, -v94
	v_exp_f32_e32 v48, v42
	v_fma_f32 v42, v49, s33, -v94
	v_exp_f32_e32 v49, v42
	v_fma_f32 v42, v50, s33, -v94
	v_exp_f32_e32 v50, v42
	v_fma_f32 v42, v51, s33, -v94
	v_exp_f32_e32 v51, v42
	v_fma_f32 v42, v52, s33, -v94
	v_exp_f32_e32 v52, v42
	v_fma_f32 v42, v53, s33, -v94
	v_exp_f32_e32 v53, v42
	v_fma_f32 v42, v54, s33, -v94
	v_exp_f32_e32 v54, v42
	v_fma_f32 v42, v55, s33, -v94
	v_exp_f32_e32 v55, v42
	v_fma_f32 v42, v56, s33, -v94
	v_exp_f32_e32 v56, v42
	v_fma_f32 v42, v57, s33, -v94
	v_exp_f32_e32 v57, v42
	ds_read_b64_tr_b16 v[42:43], v65 offset:40960
	ds_read_b64_tr_b16 v[44:45], v65 offset:43008
	v_cvt_pk_bf16_f32 v96, v89, v90
	v_cvt_pk_bf16_f32 v97, v91, v92
	v_cvt_pk_bf16_f32 v98, v93, v47
	v_cvt_pk_bf16_f32 v99, v48, v49
	v_cvt_pk_bf16_f32 v100, v50, v51
	v_cvt_pk_bf16_f32 v101, v52, v53
	s_waitcnt lgkmcnt(0)
	v_mfma_f32_16x16x32_bf16 v[38:41], v[42:45], v[96:99], v[38:41]
	ds_read_b64_tr_b16 v[42:43], v65 offset:45056
	ds_read_b64_tr_b16 v[44:45], v65 offset:47104
	v_cvt_pk_bf16_f32 v102, v54, v55
	v_cvt_pk_bf16_f32 v103, v56, v57
	s_waitcnt lgkmcnt(0)
	s_nop 0
	v_mfma_f32_16x16x32_bf16 v[38:41], v[42:45], v[100:103], v[38:41]
	ds_read_b64_tr_b16 v[42:43], v64 offset:40960
	ds_read_b64_tr_b16 v[44:45], v64 offset:43008
	s_waitcnt lgkmcnt(0)
	v_mfma_f32_16x16x32_bf16 v[30:33], v[42:45], v[96:99], v[30:33]
	ds_read_b64_tr_b16 v[42:43], v64 offset:45056
	ds_read_b64_tr_b16 v[44:45], v64 offset:47104
	s_waitcnt lgkmcnt(0)
	v_mfma_f32_16x16x32_bf16 v[42:45], v[42:45], v[100:103], v[30:33]
	s_nop 3
	ds_read_b64_tr_b16 v[30:31], v63 offset:40960
	ds_read_b64_tr_b16 v[32:33], v63 offset:43008
	s_waitcnt lgkmcnt(0)
	v_mfma_f32_16x16x32_bf16 v[30:33], v[30:33], v[96:99], v[34:37]
	s_nop 2
	ds_read_b64_tr_b16 v[34:35], v63 offset:45056
	ds_read_b64_tr_b16 v[36:37], v63 offset:47104
	s_waitcnt lgkmcnt(0)
	v_mfma_f32_16x16x32_bf16 v[30:33], v[34:37], v[100:103], v[30:33]
	ds_read_b64_tr_b16 v[34:35], v61 offset:40960
	ds_read_b64_tr_b16 v[36:37], v61 offset:43008
	s_waitcnt lgkmcnt(0)
	v_mfma_f32_16x16x32_bf16 v[26:29], v[34:37], v[96:99], v[26:29]
	ds_read_b64_tr_b16 v[34:35], v61 offset:45056
	ds_read_b64_tr_b16 v[36:37], v61 offset:47104
	s_waitcnt lgkmcnt(0)
	s_barrier
	s_waitcnt vmcnt(0)
	ds_write_b128 v85, v[10:13]
	ds_write_b128 v86, v[14:17]
	ds_write_b128 v87, v[18:21] offset:32768
	ds_write_b128 v88, v[22:25] offset:32768
	s_waitcnt lgkmcnt(0)
	s_barrier
	ds_read_b128 v[10:13], v67
	ds_read_b128 v[14:17], v66
	ds_read_b128 v[18:21], v66 offset:2048
	s_waitcnt lgkmcnt(2)
	v_mfma_f32_16x16x32_bf16 v[10:13], v[10:13], v[6:9], 0
	ds_read_b128 v[22:25], v66 offset:4096
	s_waitcnt lgkmcnt(2)
	v_mfma_f32_16x16x32_bf16 v[10:13], v[14:17], v[2:5], v[10:13]
	ds_read_b128 v[14:17], v67 offset:2048
	s_waitcnt lgkmcnt(0)
	v_mfma_f32_16x16x32_bf16 v[14:17], v[14:17], v[6:9], 0
	v_mfma_f32_16x16x32_bf16 v[18:21], v[18:21], v[2:5], v[14:17]
	s_nop 6
	ds_read_b128 v[14:17], v67 offset:4096
	s_waitcnt lgkmcnt(0)
	v_mfma_f32_16x16x32_bf16 v[14:17], v[14:17], v[6:9], 0
	v_mfma_f32_16x16x32_bf16 v[26:29], v[34:37], v[100:103], v[26:29]
	ds_read_b128 v[34:37], v66 offset:6144
	v_mfma_f32_16x16x32_bf16 v[14:17], v[22:25], v[2:5], v[14:17]
	ds_read_b128 v[22:25], v67 offset:6144
	s_waitcnt lgkmcnt(0)
	v_mfma_f32_16x16x32_bf16 v[22:25], v[22:25], v[6:9], 0
	v_mfma_f32_16x16x32_bf16 v[22:25], v[34:37], v[2:5], v[22:25]
	v_max_f32_e32 v34, v11, v11
	v_max_f32_e32 v35, v10, v10
	v_max_f32_e32 v34, v35, v34
	v_max3_f32 v34, v34, v12, v13
	v_max3_f32 v34, v34, v18, v19
	v_max3_f32 v34, v34, v20, v21
	v_max3_f32 v34, v34, v14, v15
	v_max3_f32 v34, v34, v16, v17
	v_max3_f32 v34, v34, v22, v23
	v_max3_f32 v34, v34, v24, v25
	v_mov_b32_e32 v35, v34
	s_waitcnt lgkmcnt(0)
	s_nop 0
	v_permlane16_swap_b32_e32 v34, v35
	v_max_f32_e32 v34, v34, v35
	v_mov_b32_e32 v35, v34
	s_nop 1
	v_permlane32_swap_b32_e32 v34, v35
	v_max_f32_e32 v34, v34, v35
	v_mul_f32_e32 v34, 0x3fb8aa3b, v34
	v_max_f32_e32 v35, v94, v94
	v_max_f32_e32 v106, v35, v34
	v_sub_f32_e32 v34, v94, v106
	v_exp_f32_e32 v46, v34
	s_nop 0
	v_cmp_neq_f32_e32 vcc, 1.0, v46
	s_cbranch_vccz .LBB0_413
	v_pk_mul_f32 v[40:41], v[40:41], v[46:47] op_sel_hi:[1,0]
	v_pk_mul_f32 v[38:39], v[38:39], v[46:47] op_sel_hi:[1,0]
	v_pk_mul_f32 v[44:45], v[44:45], v[46:47] op_sel_hi:[1,0]
	v_pk_mul_f32 v[42:43], v[42:43], v[46:47] op_sel_hi:[1,0]
	v_pk_mul_f32 v[32:33], v[32:33], v[46:47] op_sel_hi:[1,0]
	v_pk_mul_f32 v[30:31], v[30:31], v[46:47] op_sel_hi:[1,0]
	v_pk_mul_f32 v[28:29], v[28:29], v[46:47] op_sel_hi:[1,0]
	v_pk_mul_f32 v[26:27], v[26:27], v[46:47] op_sel_hi:[1,0]
.LBB0_413:
	v_fma_f32 v10, v10, s33, -v106
	v_exp_f32_e32 v85, v10
	v_fma_f32 v10, v11, s33, -v106
	v_exp_f32_e32 v86, v10
	v_fma_f32 v10, v12, s33, -v106
	v_exp_f32_e32 v87, v10
	v_fma_f32 v10, v13, s33, -v106
	v_exp_f32_e32 v88, v10
	v_fma_f32 v10, v18, s33, -v106
	v_exp_f32_e32 v94, v10
	v_fma_f32 v10, v19, s33, -v106
	v_exp_f32_e32 v95, v10
	v_fma_f32 v10, v20, s33, -v106
	v_exp_f32_e32 v96, v10
	v_fma_f32 v10, v21, s33, -v106
	v_exp_f32_e32 v97, v10
	v_fma_f32 v10, v14, s33, -v106
	v_exp_f32_e32 v99, v10
	v_fma_f32 v10, v15, s33, -v106
	v_exp_f32_e32 v100, v10
	v_fma_f32 v10, v16, s33, -v106
	v_exp_f32_e32 v101, v10
	v_fma_f32 v10, v17, s33, -v106
	v_exp_f32_e32 v102, v10
	v_fma_f32 v10, v22, s33, -v106
	v_exp_f32_e32 v103, v10
	v_fma_f32 v10, v23, s33, -v106
	v_exp_f32_e32 v104, v10
	v_fma_f32 v10, v24, s33, -v106
	v_exp_f32_e32 v105, v10
	v_fma_f32 v10, v25, s33, -v106
	v_exp_f32_e32 v98, v10
	ds_read_b64_tr_b16 v[10:11], v65 offset:32768
	ds_read_b64_tr_b16 v[12:13], v65 offset:34816
	v_cvt_pk_bf16_f32 v14, v85, v86
	v_cvt_pk_bf16_f32 v15, v87, v88
	v_cvt_pk_bf16_f32 v16, v94, v95
	v_cvt_pk_bf16_f32 v17, v96, v97
	ds_read_b64_tr_b16 v[18:19], v65 offset:36864
	ds_read_b64_tr_b16 v[20:21], v65 offset:38912
	s_waitcnt lgkmcnt(2)
	v_mfma_f32_16x16x32_bf16 v[10:13], v[10:13], v[14:17], v[38:41]
	v_cvt_pk_bf16_f32 v34, v99, v100
	v_cvt_pk_bf16_f32 v35, v101, v102
	v_cvt_pk_bf16_f32 v36, v103, v104
	v_cvt_pk_bf16_f32 v37, v105, v98
	s_waitcnt lgkmcnt(0)
	s_nop 0
	v_mfma_f32_16x16x32_bf16 v[10:13], v[18:21], v[34:37], v[10:13]
	ds_read_b64_tr_b16 v[18:19], v64 offset:32768
	ds_read_b64_tr_b16 v[20:21], v64 offset:34816
	ds_read_b64_tr_b16 v[22:23], v64 offset:36864
	ds_read_b64_tr_b16 v[24:25], v64 offset:38912
	s_waitcnt lgkmcnt(2)
	v_mfma_f32_16x16x32_bf16 v[18:21], v[18:21], v[14:17], v[42:45]
	s_waitcnt lgkmcnt(0)
	v_mfma_f32_16x16x32_bf16 v[22:25], v[22:25], v[34:37], v[18:21]
	s_nop 5
	ds_read_b64_tr_b16 v[18:19], v63 offset:32768
	ds_read_b64_tr_b16 v[20:21], v63 offset:34816
	s_waitcnt lgkmcnt(0)
	v_mfma_f32_16x16x32_bf16 v[18:21], v[18:21], v[14:17], v[30:33]
	s_nop 2
	ds_read_b64_tr_b16 v[30:31], v63 offset:36864
	ds_read_b64_tr_b16 v[32:33], v63 offset:38912
	s_waitcnt lgkmcnt(0)
	v_mfma_f32_16x16x32_bf16 v[18:21], v[30:33], v[34:37], v[18:21]
	ds_read_b64_tr_b16 v[30:31], v61 offset:32768
	ds_read_b64_tr_b16 v[32:33], v61 offset:34816
	s_waitcnt lgkmcnt(0)
	v_mfma_f32_16x16x32_bf16 v[14:17], v[30:33], v[14:17], v[26:29]
	s_nop 2
	ds_read_b64_tr_b16 v[26:27], v61 offset:36864
	ds_read_b64_tr_b16 v[28:29], v61 offset:38912
	ds_read_b128 v[30:33], v66 offset:8192
	ds_read_b128 v[38:41], v66 offset:12288
	s_waitcnt lgkmcnt(2)
	v_mfma_f32_16x16x32_bf16 v[14:17], v[26:29], v[34:37], v[14:17]
	ds_read_b128 v[26:29], v67 offset:8192
	ds_read_b128 v[34:37], v66 offset:10240
	s_waitcnt lgkmcnt(1)
	v_mfma_f32_16x16x32_bf16 v[26:29], v[26:29], v[6:9], 0
	v_mfma_f32_16x16x32_bf16 v[26:29], v[30:33], v[2:5], v[26:29]
	ds_read_b128 v[30:33], v67 offset:10240
	s_waitcnt lgkmcnt(0)
	v_mfma_f32_16x16x32_bf16 v[30:33], v[30:33], v[6:9], 0
	v_mfma_f32_16x16x32_bf16 v[34:37], v[34:37], v[2:5], v[30:33]
	s_nop 6
	ds_read_b128 v[30:33], v67 offset:12288
	s_waitcnt lgkmcnt(0)
	v_mfma_f32_16x16x32_bf16 v[30:33], v[30:33], v[6:9], 0
	v_mfma_f32_16x16x32_bf16 v[30:33], v[38:41], v[2:5], v[30:33]
	ds_read_b128 v[38:41], v67 offset:14336
	s_waitcnt lgkmcnt(0)
	v_mfma_f32_16x16x32_bf16 v[6:9], v[38:41], v[6:9], 0
	ds_read_b128 v[38:41], v66 offset:14336
	s_waitcnt lgkmcnt(0)
	v_mfma_f32_16x16x32_bf16 v[2:5], v[38:41], v[2:5], v[6:9]
	s_nop 4
	v_max_f32_e32 v6, v27, v27
	v_max_f32_e32 v7, v26, v26
	v_max_f32_e32 v6, v7, v6
	v_max3_f32 v6, v6, v28, v29
	v_max3_f32 v6, v6, v34, v35
	v_max3_f32 v6, v6, v36, v37
	v_max3_f32 v6, v6, v30, v31
	v_max3_f32 v6, v6, v32, v33
	v_max3_f32 v6, v6, v2, v3
	v_max3_f32 v6, v6, v4, v5
	v_mov_b32_e32 v7, v6
	s_waitcnt lgkmcnt(0)
	s_nop 0
	v_permlane16_swap_b32_e32 v6, v7
	v_max_f32_e32 v6, v6, v7
	v_mov_b32_e32 v7, v6
	s_nop 1
	v_permlane32_swap_b32_e32 v6, v7
	v_max_f32_e32 v6, v6, v7
	v_mul_f32_e32 v6, 0x3fb8aa3b, v6
	v_max_f32_e32 v7, v106, v106
	v_max_f32_e32 v7, v7, v6
	v_sub_f32_e32 v6, v106, v7
	v_exp_f32_e32 v6, v6
	s_nop 0
	v_cmp_neq_f32_e32 vcc, 1.0, v6
	s_cbranch_vccz .LBB0_415
	v_pk_mul_f32 v[12:13], v[12:13], v[6:7] op_sel_hi:[1,0]
	v_pk_mul_f32 v[10:11], v[10:11], v[6:7] op_sel_hi:[1,0]
	v_pk_mul_f32 v[24:25], v[24:25], v[6:7] op_sel_hi:[1,0]
	v_pk_mul_f32 v[22:23], v[22:23], v[6:7] op_sel_hi:[1,0]
	v_pk_mul_f32 v[20:21], v[20:21], v[6:7] op_sel_hi:[1,0]
	v_pk_mul_f32 v[18:19], v[18:19], v[6:7] op_sel_hi:[1,0]
	v_pk_mul_f32 v[16:17], v[16:17], v[6:7] op_sel_hi:[1,0]
	v_pk_mul_f32 v[14:15], v[14:15], v[6:7] op_sel_hi:[1,0]

.LBB0_430:
	v_max_f32_e32 v0, v45, v45
	v_max_f32_e32 v3, v44, v44
	v_max_f32_e32 v0, v3, v0
	v_max3_f32 v0, v0, v46, v47
	v_max3_f32 v0, v0, v52, v53
	v_max3_f32 v0, v0, v54, v55
	v_max3_f32 v0, v0, v48, v49
	v_max3_f32 v0, v0, v50, v51
	v_max3_f32 v0, v0, v56, v57
	v_max3_f32 v0, v0, v58, v59
	v_mov_b32_e32 v3, v0
	s_waitcnt lgkmcnt(0)
	s_nop 0
	v_permlane16_swap_b32_e32 v0, v3
	v_max_f32_e32 v0, v0, v3
	v_mov_b32_e32 v3, v0
	s_nop 1
	v_permlane32_swap_b32_e32 v0, v3
	v_max_f32_e32 v0, v0, v3
	v_mul_f32_e32 v0, 0x3fb8aa3b, v0
	v_max_f32_e32 v3, v80, v80
	v_max_f32_e32 v3, v3, v0
	v_sub_f32_e32 v0, v80, v3
	v_exp_f32_e32 v0, v0
	s_nop 0
	v_cmp_neq_f32_e32 vcc, 1.0, v0
	s_cbranch_vccz .LBB0_432
	v_pk_mul_f32 v[42:43], v[42:43], v[0:1] op_sel_hi:[1,0]
	v_pk_mul_f32 v[40:41], v[40:41], v[0:1] op_sel_hi:[1,0]
	v_pk_mul_f32 v[38:39], v[38:39], v[0:1] op_sel_hi:[1,0]
	v_pk_mul_f32 v[36:37], v[36:37], v[0:1] op_sel_hi:[1,0]
	v_pk_mul_f32 v[34:35], v[34:35], v[0:1] op_sel_hi:[1,0]
	v_pk_mul_f32 v[32:33], v[32:33], v[0:1] op_sel_hi:[1,0]
	v_pk_mul_f32 v[30:31], v[30:31], v[0:1] op_sel_hi:[1,0]
	v_pk_mul_f32 v[28:29], v[28:29], v[0:1] op_sel_hi:[1,0]

.LBB0_434:
	v_max_f32_e32 v2, v57, v57
	v_max_f32_e32 v80, v56, v56
	v_max_f32_e32 v2, v80, v2
	v_max3_f32 v2, v2, v58, v59
	v_max3_f32 v2, v2, v52, v53
	v_max3_f32 v2, v2, v54, v55
	v_max3_f32 v2, v2, v44, v45
	v_max3_f32 v2, v2, v46, v47
	v_max3_f32 v2, v2, v48, v49
	v_max3_f32 v2, v2, v50, v51
	v_mov_b32_e32 v80, v2
	s_waitcnt lgkmcnt(0)
	s_nop 0
	v_permlane16_swap_b32_e32 v2, v80
	v_max_f32_e32 v2, v2, v80
	v_mov_b32_e32 v80, v2
	s_nop 1
	v_permlane32_swap_b32_e32 v2, v80
	v_max_f32_e32 v2, v2, v80
	v_mul_f32_e32 v2, 0x3fb8aa3b, v2
	v_max_f32_e32 v80, v3, v3
	v_max_f32_e32 v80, v80, v2
	v_sub_f32_e32 v2, v3, v80
	v_exp_f32_e32 v2, v2
	s_nop 0
	v_cmp_neq_f32_e32 vcc, 1.0, v2
	s_cbranch_vccz .LBB0_436
	v_pk_mul_f32 v[42:43], v[42:43], v[2:3] op_sel_hi:[1,0]
	v_pk_mul_f32 v[40:41], v[40:41], v[2:3] op_sel_hi:[1,0]
	v_pk_mul_f32 v[38:39], v[38:39], v[2:3] op_sel_hi:[1,0]
	v_pk_mul_f32 v[36:37], v[36:37], v[2:3] op_sel_hi:[1,0]
	v_pk_mul_f32 v[34:35], v[34:35], v[2:3] op_sel_hi:[1,0]
	v_pk_mul_f32 v[32:33], v[32:33], v[2:3] op_sel_hi:[1,0]
	v_pk_mul_f32 v[30:31], v[30:31], v[2:3] op_sel_hi:[1,0]
	v_pk_mul_f32 v[28:29], v[28:29], v[2:3] op_sel_hi:[1,0]

.LBB0_445:
	ds_read_b128 v[116:119], v176
	ds_read_b128 v[120:123], v177
	s_waitcnt lgkmcnt(0)
	v_mfma_f32_16x16x32_bf16 v[116:119], v[116:119], v[4:7], 0
	ds_read_b128 v[124:127], v177 offset:4096
	ds_read_b128 v[128:131], v177 offset:8192
	ds_read_b128 v[132:135], v177 offset:12288
	v_mfma_f32_16x16x32_bf16 v[116:119], v[120:123], v[8:11], v[116:119]
	ds_read_b128 v[120:123], v176 offset:4096
	s_waitcnt lgkmcnt(0)
	v_mfma_f32_16x16x32_bf16 v[120:123], v[120:123], v[4:7], 0
	s_nop 4
	v_max_f32_e32 v0, v117, v117
	v_max_f32_e32 v2, v116, v116
	v_max_f32_e32 v0, v2, v0
	v_mfma_f32_16x16x32_bf16 v[120:123], v[124:127], v[8:11], v[120:123]
	ds_read_b128 v[124:127], v176 offset:8192
	v_max3_f32 v0, v0, v118, v119
	s_waitcnt lgkmcnt(0)
	v_mfma_f32_16x16x32_bf16 v[124:127], v[124:127], v[4:7], 0
	s_nop 3
	v_max3_f32 v0, v0, v120, v121
	v_max3_f32 v0, v0, v122, v123
	v_mfma_f32_16x16x32_bf16 v[124:127], v[128:131], v[8:11], v[124:127]
	ds_read_b128 v[128:131], v176 offset:12288
	s_waitcnt lgkmcnt(0)
	v_mfma_f32_16x16x32_bf16 v[128:131], v[128:131], v[4:7], 0
	s_nop 4
	v_max3_f32 v0, v0, v124, v125
	v_max3_f32 v0, v0, v126, v127
	v_mfma_f32_16x16x32_bf16 v[128:131], v[132:135], v[8:11], v[128:131]
	s_nop 7
	v_max3_f32 v0, v0, v128, v129
	v_max3_f32 v0, v0, v130, v131
	v_mov_b32_e32 v2, v0
	s_waitcnt lgkmcnt(0)
	s_nop 0
	v_permlane16_swap_b32_e32 v0, v2
	v_max_f32_e32 v0, v0, v2
	v_mov_b32_e32 v2, v0
	s_nop 1
	v_permlane32_swap_b32_e32 v0, v2
	v_max_f32_e32 v0, v0, v2
	v_mul_f32_e32 v0, 0x3fb8aa3b, v0
	v_max_f32_e32 v2, v190, v190
	v_max_f32_e32 v164, v2, v0
	v_sub_f32_e32 v0, v190, v164
	v_exp_f32_e32 v0, v0
	s_nop 0
	v_cmp_neq_f32_e32 vcc, 1.0, v0
	s_cbranch_vccz .LBB0_447
	v_pk_mul_f32 v[66:67], v[66:67], v[0:1] op_sel_hi:[1,0]
	v_pk_mul_f32 v[64:65], v[64:65], v[0:1] op_sel_hi:[1,0]
	v_pk_mul_f32 v[58:59], v[58:59], v[0:1] op_sel_hi:[1,0]
	v_pk_mul_f32 v[56:57], v[56:57], v[0:1] op_sel_hi:[1,0]
	v_pk_mul_f32 v[74:75], v[74:75], v[0:1] op_sel_hi:[1,0]
	v_pk_mul_f32 v[72:73], v[72:73], v[0:1] op_sel_hi:[1,0]
	v_pk_mul_f32 v[82:83], v[82:83], v[0:1] op_sel_hi:[1,0]
	v_pk_mul_f32 v[80:81], v[80:81], v[0:1] op_sel_hi:[1,0]
	v_pk_mul_f32 v[90:91], v[90:91], v[0:1] op_sel_hi:[1,0]
	v_pk_mul_f32 v[88:89], v[88:89], v[0:1] op_sel_hi:[1,0]
	v_pk_mul_f32 v[106:107], v[106:107], v[0:1] op_sel_hi:[1,0]
	v_pk_mul_f32 v[104:105], v[104:105], v[0:1] op_sel_hi:[1,0]
	v_pk_mul_f32 v[114:115], v[114:115], v[0:1] op_sel_hi:[1,0]
	v_pk_mul_f32 v[112:113], v[112:113], v[0:1] op_sel_hi:[1,0]
	v_pk_mul_f32 v[94:95], v[94:95], v[0:1] op_sel_hi:[1,0]
	v_pk_mul_f32 v[92:93], v[92:93], v[0:1] op_sel_hi:[1,0]
.LBB0_447:
	ds_read_b128 v[132:135], v178
	ds_read_b128 v[136:139], v179
	s_waitcnt lgkmcnt(0)
	v_mfma_f32_16x16x32_bf16 v[132:135], v[132:135], v[12:15], 0
	ds_read_b128 v[140:143], v179 offset:4096
	ds_read_b128 v[144:147], v179 offset:8192
	ds_read_b128 v[190:193], v179 offset:12288
	v_mfma_f32_16x16x32_bf16 v[132:135], v[136:139], v[16:19], v[132:135]
	ds_read_b128 v[136:139], v178 offset:4096
	s_waitcnt lgkmcnt(0)
	v_mfma_f32_16x16x32_bf16 v[136:139], v[136:139], v[12:15], 0
	s_nop 4
	v_max_f32_e32 v2, v133, v133
	v_max_f32_e32 v166, v132, v132
	v_max_f32_e32 v2, v166, v2
	v_mfma_f32_16x16x32_bf16 v[136:139], v[140:143], v[16:19], v[136:139]
	ds_read_b128 v[140:143], v178 offset:8192
	v_max3_f32 v2, v2, v134, v135
	s_waitcnt lgkmcnt(0)
	v_mfma_f32_16x16x32_bf16 v[140:143], v[140:143], v[12:15], 0
	s_nop 3
	v_max3_f32 v2, v2, v136, v137
	v_max3_f32 v2, v2, v138, v139
	v_mfma_f32_16x16x32_bf16 v[140:143], v[144:147], v[16:19], v[140:143]
	ds_read_b128 v[144:147], v178 offset:12288
	s_waitcnt lgkmcnt(0)
	v_mfma_f32_16x16x32_bf16 v[144:147], v[144:147], v[12:15], 0
	s_nop 4
	v_max3_f32 v2, v2, v140, v141
	v_max3_f32 v2, v2, v142, v143
	v_mfma_f32_16x16x32_bf16 v[144:147], v[190:193], v[16:19], v[144:147]
	s_nop 7
	v_max3_f32 v2, v2, v144, v145
	v_max3_f32 v2, v2, v146, v147
	v_mov_b32_e32 v166, v2
	s_waitcnt lgkmcnt(0)
	s_nop 0
	v_permlane16_swap_b32_e32 v2, v166
	v_max_f32_e32 v2, v2, v166
	v_mov_b32_e32 v166, v2
	s_nop 1
	v_permlane32_swap_b32_e32 v2, v166
	v_max_f32_e32 v2, v2, v166
	v_mul_f32_e32 v2, 0x3fb8aa3b, v2
	v_max_f32_e32 v166, v189, v189
	v_max_f32_e32 v166, v166, v2
	v_sub_f32_e32 v2, v189, v166
	v_exp_f32_e32 v2, v2
	s_nop 0
	v_cmp_neq_f32_e32 vcc, 1.0, v2
	s_cbranch_vccz .LBB0_449
	v_pk_mul_f32 v[62:63], v[62:63], v[2:3] op_sel_hi:[1,0]
	v_pk_mul_f32 v[60:61], v[60:61], v[2:3] op_sel_hi:[1,0]
	v_pk_mul_f32 v[54:55], v[54:55], v[2:3] op_sel_hi:[1,0]
	v_pk_mul_f32 v[52:53], v[52:53], v[2:3] op_sel_hi:[1,0]
	v_pk_mul_f32 v[70:71], v[70:71], v[2:3] op_sel_hi:[1,0]
	v_pk_mul_f32 v[68:69], v[68:69], v[2:3] op_sel_hi:[1,0]
	v_pk_mul_f32 v[78:79], v[78:79], v[2:3] op_sel_hi:[1,0]
	v_pk_mul_f32 v[76:77], v[76:77], v[2:3] op_sel_hi:[1,0]
	v_pk_mul_f32 v[86:87], v[86:87], v[2:3] op_sel_hi:[1,0]
	v_pk_mul_f32 v[84:85], v[84:85], v[2:3] op_sel_hi:[1,0]
	v_pk_mul_f32 v[102:103], v[102:103], v[2:3] op_sel_hi:[1,0]
	v_pk_mul_f32 v[100:101], v[100:101], v[2:3] op_sel_hi:[1,0]
	v_pk_mul_f32 v[110:111], v[110:111], v[2:3] op_sel_hi:[1,0]
	v_pk_mul_f32 v[108:109], v[108:109], v[2:3] op_sel_hi:[1,0]
	v_pk_mul_f32 v[98:99], v[98:99], v[2:3] op_sel_hi:[1,0]
	v_pk_mul_f32 v[96:97], v[96:97], v[2:3] op_sel_hi:[1,0]
.LBB0_449:
	v_fma_f32 v116, v116, s33, -v164
	v_exp_f32_e32 v191, v116
	v_fma_f32 v116, v117, s33, -v164
	v_exp_f32_e32 v192, v116
	v_fma_f32 v116, v118, s33, -v164
	v_exp_f32_e32 v193, v116
	v_fma_f32 v116, v119, s33, -v164
	v_exp_f32_e32 v202, v116
	v_fma_f32 v116, v120, s33, -v164
	v_exp_f32_e32 v203, v116
	v_fma_f32 v116, v121, s33, -v164
	v_exp_f32_e32 v204, v116
	v_fma_f32 v116, v122, s33, -v164
	v_exp_f32_e32 v205, v116
	v_fma_f32 v116, v123, s33, -v164
	v_exp_f32_e32 v206, v116
	v_fma_f32 v116, v124, s33, -v164
	v_fma_f32 v124, v132, s33, -v166
	v_exp_f32_e32 v215, v124
	v_fma_f32 v124, v133, s33, -v166
	v_exp_f32_e32 v216, v124
	v_fma_f32 v124, v134, s33, -v166
	v_exp_f32_e32 v217, v124
	v_fma_f32 v124, v135, s33, -v166
	v_exp_f32_e32 v218, v124
	v_fma_f32 v124, v136, s33, -v166
	v_exp_f32_e32 v219, v124
	v_fma_f32 v124, v137, s33, -v166
	v_exp_f32_e32 v220, v124
	v_fma_f32 v124, v138, s33, -v166
	v_exp_f32_e32 v221, v124
	v_fma_f32 v124, v139, s33, -v166
	v_exp_f32_e32 v222, v124
	v_fma_f32 v124, v140, s33, -v166
	v_exp_f32_e32 v207, v116
	v_fma_f32 v116, v125, s33, -v164
	v_exp_f32_e32 v223, v124
	v_fma_f32 v124, v141, s33, -v166
	v_exp_f32_e32 v208, v116
	v_fma_f32 v116, v126, s33, -v164
	v_exp_f32_e32 v224, v124
	v_fma_f32 v124, v142, s33, -v166
	v_exp_f32_e32 v209, v116
	v_fma_f32 v116, v127, s33, -v164
	v_exp_f32_e32 v225, v124
	v_fma_f32 v124, v143, s33, -v166
	v_exp_f32_e32 v210, v116
	v_fma_f32 v116, v128, s33, -v164
	v_exp_f32_e32 v226, v124
	v_fma_f32 v124, v144, s33, -v166
	ds_read_b64_tr_b16 v[132:133], v180 offset:32768
	ds_read_b64_tr_b16 v[134:135], v180 offset:36864
	v_exp_f32_e32 v211, v116
	v_fma_f32 v116, v129, s33, -v164
	v_exp_f32_e32 v227, v124
	v_fma_f32 v124, v145, s33, -v166
	v_exp_f32_e32 v212, v116
	v_fma_f32 v116, v130, s33, -v164
	v_exp_f32_e32 v228, v124
	v_fma_f32 v124, v146, s33, -v166
	v_exp_f32_e32 v213, v116
	v_fma_f32 v116, v131, s33, -v164
	v_exp_f32_e32 v229, v124
	v_fma_f32 v124, v147, s33, -v166
	v_exp_f32_e32 v214, v116
	v_cvt_pk_bf16_f32 v120, v191, v192
	v_cvt_pk_bf16_f32 v121, v193, v202
	v_cvt_pk_bf16_f32 v122, v203, v204
	v_cvt_pk_bf16_f32 v123, v205, v206
	v_exp_f32_e32 v247, v124
	v_cvt_pk_bf16_f32 v128, v215, v216
	v_cvt_pk_bf16_f32 v129, v217, v218
	v_cvt_pk_bf16_f32 v130, v219, v220
	v_cvt_pk_bf16_f32 v131, v221, v222
	ds_read_b64_tr_b16 v[136:137], v180 offset:40960
	ds_read_b64_tr_b16 v[138:139], v180 offset:45056
	s_waitcnt lgkmcnt(0)
	v_mfma_f32_16x16x32_bf16 v[64:67], v[132:135], v[120:123], v[64:67]
	v_cvt_pk_bf16_f32 v116, v207, v208
	v_cvt_pk_bf16_f32 v117, v209, v210
	v_cvt_pk_bf16_f32 v118, v211, v212
	v_mfma_f32_16x16x32_bf16 v[132:135], v[132:135], v[128:131], v[60:63]
	v_cvt_pk_bf16_f32 v119, v213, v214
	v_cvt_pk_bf16_f32 v124, v223, v224
	v_cvt_pk_bf16_f32 v125, v225, v226
	v_cvt_pk_bf16_f32 v126, v227, v228
	v_cvt_pk_bf16_f32 v127, v229, v247
	v_mfma_f32_16x16x32_bf16 v[60:63], v[136:139], v[116:119], v[64:67]
	s_nop 0
	v_mfma_f32_16x16x32_bf16 v[64:67], v[136:139], v[124:127], v[132:135]
	s_nop 2
	ds_read_b64_tr_b16 v[132:133], v181 offset:32768
	ds_read_b64_tr_b16 v[134:135], v181 offset:36864
	ds_read_b64_tr_b16 v[136:137], v181 offset:40960
	ds_read_b64_tr_b16 v[138:139], v181 offset:45056
	s_waitcnt lgkmcnt(0)
	v_mfma_f32_16x16x32_bf16 v[56:59], v[132:135], v[120:123], v[56:59]
	v_mfma_f32_16x16x32_bf16 v[132:135], v[132:135], v[128:131], v[52:55]
	v_mfma_f32_16x16x32_bf16 v[52:55], v[136:139], v[116:119], v[56:59]
	v_mfma_f32_16x16x32_bf16 v[56:59], v[136:139], v[124:127], v[132:135]
	s_nop 5
	ds_read_b64_tr_b16 v[132:133], v182 offset:32768
	ds_read_b64_tr_b16 v[134:135], v182 offset:36864
	ds_read_b64_tr_b16 v[136:137], v182 offset:40960
	ds_read_b64_tr_b16 v[138:139], v182 offset:45056
	s_waitcnt lgkmcnt(0)
	v_mfma_f32_16x16x32_bf16 v[72:75], v[132:135], v[120:123], v[72:75]
	v_mfma_f32_16x16x32_bf16 v[132:135], v[132:135], v[128:131], v[68:71]
	v_mfma_f32_16x16x32_bf16 v[68:71], v[136:139], v[116:119], v[72:75]
	v_mfma_f32_16x16x32_bf16 v[72:75], v[136:139], v[124:127], v[132:135]
	s_nop 5
	ds_read_b64_tr_b16 v[132:133], v183 offset:32768
	ds_read_b64_tr_b16 v[134:135], v183 offset:36864
	ds_read_b64_tr_b16 v[136:137], v183 offset:40960
	ds_read_b64_tr_b16 v[138:139], v183 offset:45056
	s_waitcnt lgkmcnt(0)
	v_mfma_f32_16x16x32_bf16 v[80:83], v[132:135], v[120:123], v[80:83]
	v_mfma_f32_16x16x32_bf16 v[132:135], v[132:135], v[128:131], v[76:79]
	v_mfma_f32_16x16x32_bf16 v[76:79], v[136:139], v[116:119], v[80:83]
	v_mfma_f32_16x16x32_bf16 v[80:83], v[136:139], v[124:127], v[132:135]
	s_nop 5
	ds_read_b64_tr_b16 v[132:133], v184 offset:32768
	ds_read_b64_tr_b16 v[134:135], v184 offset:36864
	ds_read_b64_tr_b16 v[136:137], v184 offset:40960
	ds_read_b64_tr_b16 v[138:139], v184 offset:45056
	s_waitcnt lgkmcnt(0)
	v_mfma_f32_16x16x32_bf16 v[88:91], v[132:135], v[120:123], v[88:91]
	v_mfma_f32_16x16x32_bf16 v[132:135], v[132:135], v[128:131], v[84:87]
	v_mfma_f32_16x16x32_bf16 v[84:87], v[136:139], v[116:119], v[88:91]
	v_mfma_f32_16x16x32_bf16 v[88:91], v[136:139], v[124:127], v[132:135]
	s_nop 5
	ds_read_b64_tr_b16 v[132:133], v185 offset:32768
	ds_read_b64_tr_b16 v[134:135], v185 offset:36864
	ds_read_b64_tr_b16 v[136:137], v185 offset:40960
	ds_read_b64_tr_b16 v[138:139], v185 offset:45056
	s_waitcnt lgkmcnt(0)
	v_mfma_f32_16x16x32_bf16 v[104:107], v[132:135], v[120:123], v[104:107]
	v_mfma_f32_16x16x32_bf16 v[132:135], v[132:135], v[128:131], v[100:103]
	v_mfma_f32_16x16x32_bf16 v[100:103], v[136:139], v[116:119], v[104:107]
	v_mfma_f32_16x16x32_bf16 v[104:107], v[136:139], v[124:127], v[132:135]
	s_nop 5
	ds_read_b64_tr_b16 v[132:133], v186 offset:32768
	ds_read_b64_tr_b16 v[134:135], v186 offset:36864
	ds_read_b64_tr_b16 v[136:137], v186 offset:40960
	ds_read_b64_tr_b16 v[138:139], v186 offset:45056
	s_waitcnt lgkmcnt(0)
	v_mfma_f32_16x16x32_bf16 v[112:115], v[132:135], v[120:123], v[112:115]
	v_mfma_f32_16x16x32_bf16 v[132:135], v[132:135], v[128:131], v[108:111]
	v_mfma_f32_16x16x32_bf16 v[108:111], v[136:139], v[116:119], v[112:115]
	v_mfma_f32_16x16x32_bf16 v[112:115], v[136:139], v[124:127], v[132:135]
	s_nop 5
	ds_read_b64_tr_b16 v[132:133], v187 offset:32768
	ds_read_b64_tr_b16 v[134:135], v187 offset:36864
	s_waitcnt lgkmcnt(0)
	v_mfma_f32_16x16x32_bf16 v[92:95], v[132:135], v[120:123], v[92:95]
	ds_read_b64_tr_b16 v[120:121], v187 offset:40960
	ds_read_b64_tr_b16 v[122:123], v187 offset:45056
	v_mfma_f32_16x16x32_bf16 v[96:99], v[132:135], v[128:131], v[96:99]
	ds_read_b128 v[128:131], v177 offset:24576
	ds_read_b128 v[132:135], v177 offset:28672
	s_waitcnt lgkmcnt(0)
	v_mfma_f32_16x16x32_bf16 v[92:95], v[120:123], v[116:119], v[92:95]
	ds_read_b128 v[116:119], v176 offset:16384
	v_mfma_f32_16x16x32_bf16 v[96:99], v[120:123], v[124:127], v[96:99]
	ds_read_b128 v[120:123], v177 offset:16384
	ds_read_b128 v[124:127], v177 offset:20480
	s_waitcnt lgkmcnt(0)
	v_mfma_f32_16x16x32_bf16 v[116:119], v[116:119], v[4:7], 0
	v_mfma_f32_16x16x32_bf16 v[116:119], v[120:123], v[8:11], v[116:119]
	ds_read_b128 v[120:123], v176 offset:20480
	s_waitcnt lgkmcnt(0)
	v_mfma_f32_16x16x32_bf16 v[120:123], v[120:123], v[4:7], 0
	v_mfma_f32_16x16x32_bf16 v[124:127], v[124:127], v[8:11], v[120:123]
	s_nop 6
	ds_read_b128 v[120:123], v176 offset:24576
	s_waitcnt lgkmcnt(0)
	v_mfma_f32_16x16x32_bf16 v[120:123], v[120:123], v[4:7], 0
	v_mfma_f32_16x16x32_bf16 v[120:123], v[128:131], v[8:11], v[120:123]
	ds_read_b128 v[128:131], v176 offset:28672
	s_waitcnt lgkmcnt(0)
	v_mfma_f32_16x16x32_bf16 v[128:131], v[128:131], v[4:7], 0
	v_mfma_f32_16x16x32_bf16 v[128:131], v[132:135], v[8:11], v[128:131]
	v_max_f32_e32 v132, v117, v117
	v_max_f32_e32 v133, v116, v116
	v_max_f32_e32 v132, v133, v132
	v_max3_f32 v132, v132, v118, v119
	v_max3_f32 v132, v132, v124, v125
	v_max3_f32 v132, v132, v126, v127
	v_max3_f32 v132, v132, v120, v121
	v_max3_f32 v132, v132, v122, v123
	v_max3_f32 v132, v132, v128, v129
	v_max3_f32 v132, v132, v130, v131
	v_mov_b32_e32 v133, v132
	s_waitcnt lgkmcnt(0)
	s_nop 0
	v_permlane16_swap_b32_e32 v132, v133
	v_max_f32_e32 v132, v132, v133
	v_mov_b32_e32 v133, v132
	s_nop 1
	v_permlane32_swap_b32_e32 v132, v133
	v_max_f32_e32 v132, v132, v133
	v_mul_f32_e32 v132, 0x3fb8aa3b, v132
	v_max_f32_e32 v133, v164, v164
	v_max_f32_e32 v190, v133, v132
	v_sub_f32_e32 v132, v164, v190
	v_exp_f32_e32 v164, v132
	s_nop 0
	v_cmp_neq_f32_e32 vcc, 1.0, v164
	s_cbranch_vccz .LBB0_451
	v_pk_mul_f32 v[62:63], v[62:63], v[164:165] op_sel_hi:[1,0]
	v_pk_mul_f32 v[60:61], v[60:61], v[164:165] op_sel_hi:[1,0]
	v_pk_mul_f32 v[54:55], v[54:55], v[164:165] op_sel_hi:[1,0]
	v_pk_mul_f32 v[52:53], v[52:53], v[164:165] op_sel_hi:[1,0]
	v_pk_mul_f32 v[70:71], v[70:71], v[164:165] op_sel_hi:[1,0]
	v_pk_mul_f32 v[68:69], v[68:69], v[164:165] op_sel_hi:[1,0]
	v_pk_mul_f32 v[78:79], v[78:79], v[164:165] op_sel_hi:[1,0]
	v_pk_mul_f32 v[76:77], v[76:77], v[164:165] op_sel_hi:[1,0]
	v_pk_mul_f32 v[86:87], v[86:87], v[164:165] op_sel_hi:[1,0]
	v_pk_mul_f32 v[84:85], v[84:85], v[164:165] op_sel_hi:[1,0]
	v_pk_mul_f32 v[102:103], v[102:103], v[164:165] op_sel_hi:[1,0]
	v_pk_mul_f32 v[100:101], v[100:101], v[164:165] op_sel_hi:[1,0]
	v_pk_mul_f32 v[110:111], v[110:111], v[164:165] op_sel_hi:[1,0]
	v_pk_mul_f32 v[108:109], v[108:109], v[164:165] op_sel_hi:[1,0]
	v_pk_mul_f32 v[94:95], v[94:95], v[164:165] op_sel_hi:[1,0]
	v_pk_mul_f32 v[92:93], v[92:93], v[164:165] op_sel_hi:[1,0]
.LBB0_451:
	ds_read_b128 v[132:135], v178 offset:16384
	ds_read_b128 v[136:139], v179 offset:16384
	s_waitcnt lgkmcnt(0)
	v_mfma_f32_16x16x32_bf16 v[132:135], v[132:135], v[12:15], 0
	ds_read_b128 v[194:197], v179 offset:28672
	v_mfma_f32_16x16x32_bf16 v[144:147], v[136:139], v[16:19], v[132:135]
	ds_read_b128 v[136:139], v179 offset:20480
	s_nop 4
	ds_read_b128 v[132:135], v178 offset:20480
	s_waitcnt lgkmcnt(0)
	v_mfma_f32_16x16x32_bf16 v[132:135], v[132:135], v[12:15], 0
	v_max_f32_e32 v189, v145, v145
	v_mfma_f32_16x16x32_bf16 v[140:143], v[136:139], v[16:19], v[132:135]
	ds_read_b128 v[136:139], v179 offset:24576
	s_nop 4
	ds_read_b128 v[132:135], v178 offset:24576
	s_waitcnt lgkmcnt(0)
	v_mfma_f32_16x16x32_bf16 v[132:135], v[132:135], v[12:15], 0
	v_mfma_f32_16x16x32_bf16 v[136:139], v[136:139], v[16:19], v[132:135]
	s_nop 6
	ds_read_b128 v[132:135], v178 offset:28672
	s_waitcnt lgkmcnt(0)
	v_mfma_f32_16x16x32_bf16 v[132:135], v[132:135], v[12:15], 0
	v_mfma_f32_16x16x32_bf16 v[132:135], v[194:197], v[16:19], v[132:135]
	v_max_f32_e32 v194, v144, v144
	v_max_f32_e32 v189, v194, v189
	v_max3_f32 v189, v189, v146, v147
	v_max3_f32 v189, v189, v140, v141
	v_max3_f32 v189, v189, v142, v143
	v_max3_f32 v189, v189, v136, v137
	v_max3_f32 v189, v189, v138, v139
	s_nop 0
	v_max3_f32 v189, v189, v132, v133
	v_max3_f32 v189, v189, v134, v135
	v_mov_b32_e32 v194, v189
	s_waitcnt lgkmcnt(0)
	s_nop 0
	v_permlane16_swap_b32_e32 v189, v194
	v_max_f32_e32 v189, v189, v194
	v_mov_b32_e32 v194, v189
	s_nop 1
	v_permlane32_swap_b32_e32 v189, v194
	v_max_f32_e32 v189, v189, v194
	v_mul_f32_e32 v189, 0x3fb8aa3b, v189
	v_max_f32_e32 v194, v166, v166
	v_max_f32_e32 v189, v194, v189
	v_sub_f32_e32 v166, v166, v189
	v_exp_f32_e32 v166, v166
	s_nop 0
	v_cmp_neq_f32_e32 vcc, 1.0, v166
	s_cbranch_vccz .LBB0_453
	v_pk_mul_f32 v[66:67], v[66:67], v[166:167] op_sel_hi:[1,0]
	v_pk_mul_f32 v[64:65], v[64:65], v[166:167] op_sel_hi:[1,0]
	v_pk_mul_f32 v[58:59], v[58:59], v[166:167] op_sel_hi:[1,0]
	v_pk_mul_f32 v[56:57], v[56:57], v[166:167] op_sel_hi:[1,0]
	v_pk_mul_f32 v[74:75], v[74:75], v[166:167] op_sel_hi:[1,0]
	v_pk_mul_f32 v[72:73], v[72:73], v[166:167] op_sel_hi:[1,0]
	v_pk_mul_f32 v[82:83], v[82:83], v[166:167] op_sel_hi:[1,0]
	v_pk_mul_f32 v[80:81], v[80:81], v[166:167] op_sel_hi:[1,0]
	v_pk_mul_f32 v[90:91], v[90:91], v[166:167] op_sel_hi:[1,0]
	v_pk_mul_f32 v[88:89], v[88:89], v[166:167] op_sel_hi:[1,0]
	v_pk_mul_f32 v[106:107], v[106:107], v[166:167] op_sel_hi:[1,0]
	v_pk_mul_f32 v[104:105], v[104:105], v[166:167] op_sel_hi:[1,0]
	v_pk_mul_f32 v[114:115], v[114:115], v[166:167] op_sel_hi:[1,0]
	v_pk_mul_f32 v[112:113], v[112:113], v[166:167] op_sel_hi:[1,0]
	v_pk_mul_f32 v[98:99], v[98:99], v[166:167] op_sel_hi:[1,0]
	v_pk_mul_f32 v[96:97], v[96:97], v[166:167] op_sel_hi:[1,0]

.LBB0_505:
	ds_read_b128 v[116:119], v172
	ds_read_b128 v[120:123], v173
	s_waitcnt lgkmcnt(0)
	v_mfma_f32_16x16x32_bf16 v[116:119], v[116:119], v[4:7], 0
	ds_read_b128 v[124:127], v173 offset:4096
	ds_read_b128 v[128:131], v173 offset:8192
	ds_read_b128 v[132:135], v173 offset:12288
	v_mfma_f32_16x16x32_bf16 v[116:119], v[120:123], v[8:11], v[116:119]
	ds_read_b128 v[120:123], v172 offset:4096
	s_waitcnt lgkmcnt(0)
	v_mfma_f32_16x16x32_bf16 v[120:123], v[120:123], v[4:7], 0
	s_nop 4
	v_max_f32_e32 v0, v117, v117
	v_max_f32_e32 v2, v116, v116
	v_max_f32_e32 v0, v2, v0
	v_mfma_f32_16x16x32_bf16 v[120:123], v[124:127], v[8:11], v[120:123]
	ds_read_b128 v[124:127], v172 offset:8192
	v_max3_f32 v0, v0, v118, v119
	s_waitcnt lgkmcnt(0)
	v_mfma_f32_16x16x32_bf16 v[124:127], v[124:127], v[4:7], 0
	s_nop 3
	v_max3_f32 v0, v0, v120, v121
	v_max3_f32 v0, v0, v122, v123
	v_mfma_f32_16x16x32_bf16 v[124:127], v[128:131], v[8:11], v[124:127]
	ds_read_b128 v[128:131], v172 offset:12288
	s_waitcnt lgkmcnt(0)
	v_mfma_f32_16x16x32_bf16 v[128:131], v[128:131], v[4:7], 0
	s_nop 4
	v_max3_f32 v0, v0, v124, v125
	v_max3_f32 v0, v0, v126, v127
	v_mfma_f32_16x16x32_bf16 v[128:131], v[132:135], v[8:11], v[128:131]
	s_nop 7
	v_max3_f32 v0, v0, v128, v129
	v_max3_f32 v0, v0, v130, v131
	v_mov_b32_e32 v2, v0
	s_waitcnt lgkmcnt(0)
	s_nop 0
	v_permlane16_swap_b32_e32 v0, v2
	v_max_f32_e32 v0, v0, v2
	v_mov_b32_e32 v2, v0
	s_nop 1
	v_permlane32_swap_b32_e32 v0, v2
	v_max_f32_e32 v0, v0, v2
	v_mul_f32_e32 v0, 0x3fb8aa3b, v0
	v_max_f32_e32 v2, v186, v186
	v_max_f32_e32 v164, v2, v0
	v_sub_f32_e32 v0, v186, v164
	v_exp_f32_e32 v0, v0
	s_nop 0
	v_cmp_neq_f32_e32 vcc, 1.0, v0
	s_cbranch_vccz .LBB0_507
	v_pk_mul_f32 v[66:67], v[66:67], v[0:1] op_sel_hi:[1,0]
	v_pk_mul_f32 v[64:65], v[64:65], v[0:1] op_sel_hi:[1,0]
	v_pk_mul_f32 v[58:59], v[58:59], v[0:1] op_sel_hi:[1,0]
	v_pk_mul_f32 v[56:57], v[56:57], v[0:1] op_sel_hi:[1,0]
	v_pk_mul_f32 v[74:75], v[74:75], v[0:1] op_sel_hi:[1,0]
	v_pk_mul_f32 v[72:73], v[72:73], v[0:1] op_sel_hi:[1,0]
	v_pk_mul_f32 v[82:83], v[82:83], v[0:1] op_sel_hi:[1,0]
	v_pk_mul_f32 v[80:81], v[80:81], v[0:1] op_sel_hi:[1,0]
	v_pk_mul_f32 v[90:91], v[90:91], v[0:1] op_sel_hi:[1,0]
	v_pk_mul_f32 v[88:89], v[88:89], v[0:1] op_sel_hi:[1,0]
	v_pk_mul_f32 v[98:99], v[98:99], v[0:1] op_sel_hi:[1,0]
	v_pk_mul_f32 v[96:97], v[96:97], v[0:1] op_sel_hi:[1,0]
	v_pk_mul_f32 v[106:107], v[106:107], v[0:1] op_sel_hi:[1,0]
	v_pk_mul_f32 v[104:105], v[104:105], v[0:1] op_sel_hi:[1,0]
	v_pk_mul_f32 v[114:115], v[114:115], v[0:1] op_sel_hi:[1,0]
	v_pk_mul_f32 v[112:113], v[112:113], v[0:1] op_sel_hi:[1,0]
.LBB0_507:
	ds_read_b128 v[132:135], v174
	ds_read_b128 v[136:139], v175
	s_waitcnt lgkmcnt(0)
	v_mfma_f32_16x16x32_bf16 v[132:135], v[132:135], v[12:15], 0
	ds_read_b128 v[140:143], v175 offset:4096
	ds_read_b128 v[144:147], v175 offset:8192
	ds_read_b128 v[186:189], v175 offset:12288
	v_mfma_f32_16x16x32_bf16 v[132:135], v[136:139], v[16:19], v[132:135]
	ds_read_b128 v[136:139], v174 offset:4096
	s_waitcnt lgkmcnt(0)
	v_mfma_f32_16x16x32_bf16 v[136:139], v[136:139], v[12:15], 0
	s_nop 4
	v_max_f32_e32 v2, v133, v133
	v_max_f32_e32 v166, v132, v132
	v_max_f32_e32 v2, v166, v2
	v_mfma_f32_16x16x32_bf16 v[136:139], v[140:143], v[16:19], v[136:139]
	ds_read_b128 v[140:143], v174 offset:8192
	v_max3_f32 v2, v2, v134, v135
	s_waitcnt lgkmcnt(0)
	v_mfma_f32_16x16x32_bf16 v[140:143], v[140:143], v[12:15], 0
	s_nop 3
	v_max3_f32 v2, v2, v136, v137
	v_max3_f32 v2, v2, v138, v139
	v_mfma_f32_16x16x32_bf16 v[140:143], v[144:147], v[16:19], v[140:143]
	ds_read_b128 v[144:147], v174 offset:12288
	s_waitcnt lgkmcnt(0)
	v_mfma_f32_16x16x32_bf16 v[144:147], v[144:147], v[12:15], 0
	s_nop 4
	v_max3_f32 v2, v2, v140, v141
	v_max3_f32 v2, v2, v142, v143
	v_mfma_f32_16x16x32_bf16 v[144:147], v[186:189], v[16:19], v[144:147]
	s_nop 7
	v_max3_f32 v2, v2, v144, v145
	v_max3_f32 v2, v2, v146, v147
	v_mov_b32_e32 v166, v2
	s_waitcnt lgkmcnt(0)
	s_nop 0
	v_permlane16_swap_b32_e32 v2, v166
	v_max_f32_e32 v2, v2, v166
	v_mov_b32_e32 v166, v2
	s_nop 1
	v_permlane32_swap_b32_e32 v2, v166
	v_max_f32_e32 v2, v2, v166
	v_mul_f32_e32 v2, 0x3fb8aa3b, v2
	v_max_f32_e32 v166, v185, v185
	v_max_f32_e32 v166, v166, v2
	v_sub_f32_e32 v2, v185, v166
	v_exp_f32_e32 v2, v2
	s_nop 0
	v_cmp_neq_f32_e32 vcc, 1.0, v2
	s_cbranch_vccz .LBB0_509
	v_pk_mul_f32 v[62:63], v[62:63], v[2:3] op_sel_hi:[1,0]
	v_pk_mul_f32 v[60:61], v[60:61], v[2:3] op_sel_hi:[1,0]
	v_pk_mul_f32 v[54:55], v[54:55], v[2:3] op_sel_hi:[1,0]
	v_pk_mul_f32 v[52:53], v[52:53], v[2:3] op_sel_hi:[1,0]
	v_pk_mul_f32 v[70:71], v[70:71], v[2:3] op_sel_hi:[1,0]
	v_pk_mul_f32 v[68:69], v[68:69], v[2:3] op_sel_hi:[1,0]
	v_pk_mul_f32 v[78:79], v[78:79], v[2:3] op_sel_hi:[1,0]
	v_pk_mul_f32 v[76:77], v[76:77], v[2:3] op_sel_hi:[1,0]
	v_pk_mul_f32 v[86:87], v[86:87], v[2:3] op_sel_hi:[1,0]
	v_pk_mul_f32 v[84:85], v[84:85], v[2:3] op_sel_hi:[1,0]
	v_pk_mul_f32 v[94:95], v[94:95], v[2:3] op_sel_hi:[1,0]
	v_pk_mul_f32 v[92:93], v[92:93], v[2:3] op_sel_hi:[1,0]
	v_pk_mul_f32 v[102:103], v[102:103], v[2:3] op_sel_hi:[1,0]
	v_pk_mul_f32 v[100:101], v[100:101], v[2:3] op_sel_hi:[1,0]
	v_pk_mul_f32 v[110:111], v[110:111], v[2:3] op_sel_hi:[1,0]
	v_pk_mul_f32 v[108:109], v[108:109], v[2:3] op_sel_hi:[1,0]
.LBB0_509:
	v_fma_f32 v116, v116, s33, -v164
	v_exp_f32_e32 v187, v116
	v_fma_f32 v116, v117, s33, -v164
	v_exp_f32_e32 v188, v116
	v_fma_f32 v116, v118, s33, -v164
	v_exp_f32_e32 v189, v116
	v_fma_f32 v116, v119, s33, -v164
	v_exp_f32_e32 v190, v116
	v_fma_f32 v116, v120, s33, -v164
	v_exp_f32_e32 v191, v116
	v_fma_f32 v116, v121, s33, -v164
	v_exp_f32_e32 v192, v116
	v_fma_f32 v116, v122, s33, -v164
	v_exp_f32_e32 v193, v116
	v_fma_f32 v116, v123, s33, -v164
	v_exp_f32_e32 v202, v116
	v_fma_f32 v116, v124, s33, -v164
	v_fma_f32 v124, v132, s33, -v166
	v_exp_f32_e32 v211, v124
	v_fma_f32 v124, v133, s33, -v166
	v_exp_f32_e32 v212, v124
	v_fma_f32 v124, v134, s33, -v166
	v_exp_f32_e32 v213, v124
	v_fma_f32 v124, v135, s33, -v166
	v_exp_f32_e32 v214, v124
	v_fma_f32 v124, v136, s33, -v166
	v_exp_f32_e32 v215, v124
	v_fma_f32 v124, v137, s33, -v166
	v_exp_f32_e32 v216, v124
	v_fma_f32 v124, v138, s33, -v166
	v_exp_f32_e32 v217, v124
	v_fma_f32 v124, v139, s33, -v166
	v_exp_f32_e32 v218, v124
	v_fma_f32 v124, v140, s33, -v166
	v_exp_f32_e32 v203, v116
	v_fma_f32 v116, v125, s33, -v164
	v_exp_f32_e32 v219, v124
	v_fma_f32 v124, v141, s33, -v166
	v_exp_f32_e32 v204, v116
	v_fma_f32 v116, v126, s33, -v164
	v_exp_f32_e32 v220, v124
	v_fma_f32 v124, v142, s33, -v166
	v_exp_f32_e32 v205, v116
	v_fma_f32 v116, v127, s33, -v164
	v_exp_f32_e32 v221, v124
	v_fma_f32 v124, v143, s33, -v166
	v_exp_f32_e32 v206, v116
	v_fma_f32 v116, v128, s33, -v164
	v_exp_f32_e32 v222, v124
	v_fma_f32 v124, v144, s33, -v166
	ds_read_b64_tr_b16 v[132:133], v176 offset:32768
	ds_read_b64_tr_b16 v[134:135], v176 offset:36864
	v_exp_f32_e32 v207, v116
	v_fma_f32 v116, v129, s33, -v164
	v_exp_f32_e32 v223, v124
	v_fma_f32 v124, v145, s33, -v166
	v_exp_f32_e32 v208, v116
	v_fma_f32 v116, v130, s33, -v164
	v_exp_f32_e32 v224, v124
	v_fma_f32 v124, v146, s33, -v166
	v_exp_f32_e32 v209, v116
	v_fma_f32 v116, v131, s33, -v164
	v_exp_f32_e32 v225, v124
	v_fma_f32 v124, v147, s33, -v166
	v_exp_f32_e32 v210, v116
	v_cvt_pk_bf16_f32 v120, v187, v188
	v_cvt_pk_bf16_f32 v121, v189, v190
	v_cvt_pk_bf16_f32 v122, v191, v192
	v_cvt_pk_bf16_f32 v123, v193, v202
	v_exp_f32_e32 v226, v124
	v_cvt_pk_bf16_f32 v128, v211, v212
	v_cvt_pk_bf16_f32 v129, v213, v214
	v_cvt_pk_bf16_f32 v130, v215, v216
	v_cvt_pk_bf16_f32 v131, v217, v218
	ds_read_b64_tr_b16 v[136:137], v176 offset:40960
	ds_read_b64_tr_b16 v[138:139], v176 offset:45056
	s_waitcnt lgkmcnt(0)
	v_mfma_f32_16x16x32_bf16 v[64:67], v[132:135], v[120:123], v[64:67]
	v_cvt_pk_bf16_f32 v116, v203, v204
	v_cvt_pk_bf16_f32 v117, v205, v206
	v_cvt_pk_bf16_f32 v118, v207, v208
	v_mfma_f32_16x16x32_bf16 v[132:135], v[132:135], v[128:131], v[60:63]
	v_cvt_pk_bf16_f32 v119, v209, v210
	v_cvt_pk_bf16_f32 v124, v219, v220
	v_cvt_pk_bf16_f32 v125, v221, v222
	v_cvt_pk_bf16_f32 v126, v223, v224
	v_cvt_pk_bf16_f32 v127, v225, v226
	v_mfma_f32_16x16x32_bf16 v[60:63], v[136:139], v[116:119], v[64:67]
	s_nop 0
	v_mfma_f32_16x16x32_bf16 v[64:67], v[136:139], v[124:127], v[132:135]
	s_nop 2
	ds_read_b64_tr_b16 v[132:133], v177 offset:32768
	ds_read_b64_tr_b16 v[134:135], v177 offset:36864
	ds_read_b64_tr_b16 v[136:137], v177 offset:40960
	ds_read_b64_tr_b16 v[138:139], v177 offset:45056
	s_waitcnt lgkmcnt(0)
	v_mfma_f32_16x16x32_bf16 v[56:59], v[132:135], v[120:123], v[56:59]
	v_mfma_f32_16x16x32_bf16 v[132:135], v[132:135], v[128:131], v[52:55]
	v_mfma_f32_16x16x32_bf16 v[52:55], v[136:139], v[116:119], v[56:59]
	v_mfma_f32_16x16x32_bf16 v[56:59], v[136:139], v[124:127], v[132:135]
	s_nop 5
	ds_read_b64_tr_b16 v[132:133], v178 offset:32768
	ds_read_b64_tr_b16 v[134:135], v178 offset:36864
	ds_read_b64_tr_b16 v[136:137], v178 offset:40960
	ds_read_b64_tr_b16 v[138:139], v178 offset:45056
	s_waitcnt lgkmcnt(0)
	v_mfma_f32_16x16x32_bf16 v[72:75], v[132:135], v[120:123], v[72:75]
	v_mfma_f32_16x16x32_bf16 v[132:135], v[132:135], v[128:131], v[68:71]
	v_mfma_f32_16x16x32_bf16 v[68:71], v[136:139], v[116:119], v[72:75]
	v_mfma_f32_16x16x32_bf16 v[72:75], v[136:139], v[124:127], v[132:135]
	s_nop 5
	ds_read_b64_tr_b16 v[132:133], v179 offset:32768
	ds_read_b64_tr_b16 v[134:135], v179 offset:36864
	ds_read_b64_tr_b16 v[136:137], v179 offset:40960
	ds_read_b64_tr_b16 v[138:139], v179 offset:45056
	s_waitcnt lgkmcnt(0)
	v_mfma_f32_16x16x32_bf16 v[80:83], v[132:135], v[120:123], v[80:83]
	v_mfma_f32_16x16x32_bf16 v[132:135], v[132:135], v[128:131], v[76:79]
	v_mfma_f32_16x16x32_bf16 v[76:79], v[136:139], v[116:119], v[80:83]
	v_mfma_f32_16x16x32_bf16 v[80:83], v[136:139], v[124:127], v[132:135]
	s_nop 5
	ds_read_b64_tr_b16 v[132:133], v180 offset:32768
	ds_read_b64_tr_b16 v[134:135], v180 offset:36864
	ds_read_b64_tr_b16 v[136:137], v180 offset:40960
	ds_read_b64_tr_b16 v[138:139], v180 offset:45056
	s_waitcnt lgkmcnt(0)
	v_mfma_f32_16x16x32_bf16 v[88:91], v[132:135], v[120:123], v[88:91]
	v_mfma_f32_16x16x32_bf16 v[132:135], v[132:135], v[128:131], v[84:87]
	v_mfma_f32_16x16x32_bf16 v[84:87], v[136:139], v[116:119], v[88:91]
	v_mfma_f32_16x16x32_bf16 v[88:91], v[136:139], v[124:127], v[132:135]
	s_nop 5
	ds_read_b64_tr_b16 v[132:133], v181 offset:32768
	ds_read_b64_tr_b16 v[134:135], v181 offset:36864
	ds_read_b64_tr_b16 v[136:137], v181 offset:40960
	ds_read_b64_tr_b16 v[138:139], v181 offset:45056
	s_waitcnt lgkmcnt(0)
	v_mfma_f32_16x16x32_bf16 v[96:99], v[132:135], v[120:123], v[96:99]
	v_mfma_f32_16x16x32_bf16 v[132:135], v[132:135], v[128:131], v[92:95]
	v_mfma_f32_16x16x32_bf16 v[92:95], v[136:139], v[116:119], v[96:99]
	v_mfma_f32_16x16x32_bf16 v[96:99], v[136:139], v[124:127], v[132:135]
	s_nop 5
	ds_read_b64_tr_b16 v[132:133], v182 offset:32768
	ds_read_b64_tr_b16 v[134:135], v182 offset:36864
	ds_read_b64_tr_b16 v[136:137], v182 offset:40960
	ds_read_b64_tr_b16 v[138:139], v182 offset:45056
	s_waitcnt lgkmcnt(0)
	v_mfma_f32_16x16x32_bf16 v[104:107], v[132:135], v[120:123], v[104:107]
	v_mfma_f32_16x16x32_bf16 v[132:135], v[132:135], v[128:131], v[100:103]
	v_mfma_f32_16x16x32_bf16 v[100:103], v[136:139], v[116:119], v[104:107]
	v_mfma_f32_16x16x32_bf16 v[104:107], v[136:139], v[124:127], v[132:135]
	s_nop 5
	ds_read_b64_tr_b16 v[132:133], v183 offset:32768
	ds_read_b64_tr_b16 v[134:135], v183 offset:36864
	s_waitcnt lgkmcnt(0)
	v_mfma_f32_16x16x32_bf16 v[112:115], v[132:135], v[120:123], v[112:115]
	v_mfma_f32_16x16x32_bf16 v[120:123], v[132:135], v[128:131], v[108:111]
	ds_read_b64_tr_b16 v[128:129], v183 offset:40960
	ds_read_b64_tr_b16 v[130:131], v183 offset:45056
	ds_read_b128 v[132:135], v173 offset:28672
	s_waitcnt lgkmcnt(0)
	v_mfma_f32_16x16x32_bf16 v[108:111], v[128:131], v[116:119], v[112:115]
	ds_read_b128 v[116:119], v172 offset:16384
	v_mfma_f32_16x16x32_bf16 v[112:115], v[128:131], v[124:127], v[120:123]
	ds_read_b128 v[124:127], v173 offset:20480
	ds_read_b128 v[128:131], v173 offset:24576
	s_nop 0
	ds_read_b128 v[120:123], v173 offset:16384
	s_waitcnt lgkmcnt(0)
	v_mfma_f32_16x16x32_bf16 v[116:119], v[116:119], v[4:7], 0
	v_mfma_f32_16x16x32_bf16 v[116:119], v[120:123], v[8:11], v[116:119]
	ds_read_b128 v[120:123], v172 offset:20480
	s_waitcnt lgkmcnt(0)
	v_mfma_f32_16x16x32_bf16 v[120:123], v[120:123], v[4:7], 0
	v_mfma_f32_16x16x32_bf16 v[124:127], v[124:127], v[8:11], v[120:123]
	s_nop 6
	ds_read_b128 v[120:123], v172 offset:24576
	s_waitcnt lgkmcnt(0)
	v_mfma_f32_16x16x32_bf16 v[120:123], v[120:123], v[4:7], 0
	v_mfma_f32_16x16x32_bf16 v[120:123], v[128:131], v[8:11], v[120:123]
	ds_read_b128 v[128:131], v172 offset:28672
	s_waitcnt lgkmcnt(0)
	v_mfma_f32_16x16x32_bf16 v[128:131], v[128:131], v[4:7], 0
	v_mfma_f32_16x16x32_bf16 v[128:131], v[132:135], v[8:11], v[128:131]
	v_max_f32_e32 v132, v117, v117
	v_max_f32_e32 v133, v116, v116
	v_max_f32_e32 v132, v133, v132
	v_max3_f32 v132, v132, v118, v119
	v_max3_f32 v132, v132, v124, v125
	v_max3_f32 v132, v132, v126, v127
	v_max3_f32 v132, v132, v120, v121
	v_max3_f32 v132, v132, v122, v123
	v_max3_f32 v132, v132, v128, v129
	v_max3_f32 v132, v132, v130, v131
	v_mov_b32_e32 v133, v132
	s_waitcnt lgkmcnt(0)
	s_nop 0
	v_permlane16_swap_b32_e32 v132, v133
	v_max_f32_e32 v132, v132, v133
	v_mov_b32_e32 v133, v132
	s_nop 1
	v_permlane32_swap_b32_e32 v132, v133
	v_max_f32_e32 v132, v132, v133
	v_mul_f32_e32 v132, 0x3fb8aa3b, v132
	v_max_f32_e32 v133, v164, v164
	v_max_f32_e32 v186, v133, v132
	v_sub_f32_e32 v132, v164, v186
	v_exp_f32_e32 v164, v132
	s_nop 0
	v_cmp_neq_f32_e32 vcc, 1.0, v164
	s_cbranch_vccz .LBB0_511
	v_pk_mul_f32 v[62:63], v[62:63], v[164:165] op_sel_hi:[1,0]
	v_pk_mul_f32 v[60:61], v[60:61], v[164:165] op_sel_hi:[1,0]
	v_pk_mul_f32 v[54:55], v[54:55], v[164:165] op_sel_hi:[1,0]
	v_pk_mul_f32 v[52:53], v[52:53], v[164:165] op_sel_hi:[1,0]
	v_pk_mul_f32 v[70:71], v[70:71], v[164:165] op_sel_hi:[1,0]
	v_pk_mul_f32 v[68:69], v[68:69], v[164:165] op_sel_hi:[1,0]
	v_pk_mul_f32 v[78:79], v[78:79], v[164:165] op_sel_hi:[1,0]
	v_pk_mul_f32 v[76:77], v[76:77], v[164:165] op_sel_hi:[1,0]
	v_pk_mul_f32 v[86:87], v[86:87], v[164:165] op_sel_hi:[1,0]
	v_pk_mul_f32 v[84:85], v[84:85], v[164:165] op_sel_hi:[1,0]
	v_pk_mul_f32 v[94:95], v[94:95], v[164:165] op_sel_hi:[1,0]
	v_pk_mul_f32 v[92:93], v[92:93], v[164:165] op_sel_hi:[1,0]
	v_pk_mul_f32 v[102:103], v[102:103], v[164:165] op_sel_hi:[1,0]
	v_pk_mul_f32 v[100:101], v[100:101], v[164:165] op_sel_hi:[1,0]
	v_pk_mul_f32 v[110:111], v[110:111], v[164:165] op_sel_hi:[1,0]
	v_pk_mul_f32 v[108:109], v[108:109], v[164:165] op_sel_hi:[1,0]
.LBB0_511:
	ds_read_b128 v[132:135], v174 offset:16384
	ds_read_b128 v[136:139], v175 offset:16384
	s_waitcnt lgkmcnt(0)
	v_mfma_f32_16x16x32_bf16 v[132:135], v[132:135], v[12:15], 0
	ds_read_b128 v[194:197], v175 offset:28672
	v_mfma_f32_16x16x32_bf16 v[144:147], v[136:139], v[16:19], v[132:135]
	ds_read_b128 v[136:139], v175 offset:20480
	s_nop 4
	ds_read_b128 v[132:135], v174 offset:20480
	s_waitcnt lgkmcnt(0)
	v_mfma_f32_16x16x32_bf16 v[132:135], v[132:135], v[12:15], 0
	v_max_f32_e32 v185, v145, v145
	v_mfma_f32_16x16x32_bf16 v[140:143], v[136:139], v[16:19], v[132:135]
	ds_read_b128 v[136:139], v175 offset:24576
	s_nop 4
	ds_read_b128 v[132:135], v174 offset:24576
	s_waitcnt lgkmcnt(0)
	v_mfma_f32_16x16x32_bf16 v[132:135], v[132:135], v[12:15], 0
	v_mfma_f32_16x16x32_bf16 v[136:139], v[136:139], v[16:19], v[132:135]
	s_nop 6
	ds_read_b128 v[132:135], v174 offset:28672
	s_waitcnt lgkmcnt(0)
	v_mfma_f32_16x16x32_bf16 v[132:135], v[132:135], v[12:15], 0
	v_mfma_f32_16x16x32_bf16 v[132:135], v[194:197], v[16:19], v[132:135]
	v_max_f32_e32 v194, v144, v144
	v_max_f32_e32 v185, v194, v185
	v_max3_f32 v185, v185, v146, v147
	v_max3_f32 v185, v185, v140, v141
	v_max3_f32 v185, v185, v142, v143
	v_max3_f32 v185, v185, v136, v137
	v_max3_f32 v185, v185, v138, v139
	s_nop 0
	v_max3_f32 v185, v185, v132, v133
	v_max3_f32 v185, v185, v134, v135
	v_mov_b32_e32 v194, v185
	s_waitcnt lgkmcnt(0)
	s_nop 0
	v_permlane16_swap_b32_e32 v185, v194
	v_max_f32_e32 v185, v185, v194
	v_mov_b32_e32 v194, v185
	s_nop 1
	v_permlane32_swap_b32_e32 v185, v194
	v_max_f32_e32 v185, v185, v194
	v_mul_f32_e32 v185, 0x3fb8aa3b, v185
	v_max_f32_e32 v194, v166, v166
	v_max_f32_e32 v185, v194, v185
	v_sub_f32_e32 v166, v166, v185
	v_exp_f32_e32 v166, v166
	s_nop 0
	v_cmp_neq_f32_e32 vcc, 1.0, v166
	s_cbranch_vccz .LBB0_513
	v_pk_mul_f32 v[66:67], v[66:67], v[166:167] op_sel_hi:[1,0]
	v_pk_mul_f32 v[64:65], v[64:65], v[166:167] op_sel_hi:[1,0]
	v_pk_mul_f32 v[58:59], v[58:59], v[166:167] op_sel_hi:[1,0]
	v_pk_mul_f32 v[56:57], v[56:57], v[166:167] op_sel_hi:[1,0]
	v_pk_mul_f32 v[74:75], v[74:75], v[166:167] op_sel_hi:[1,0]
	v_pk_mul_f32 v[72:73], v[72:73], v[166:167] op_sel_hi:[1,0]
	v_pk_mul_f32 v[82:83], v[82:83], v[166:167] op_sel_hi:[1,0]
	v_pk_mul_f32 v[80:81], v[80:81], v[166:167] op_sel_hi:[1,0]
	v_pk_mul_f32 v[90:91], v[90:91], v[166:167] op_sel_hi:[1,0]
	v_pk_mul_f32 v[88:89], v[88:89], v[166:167] op_sel_hi:[1,0]
	v_pk_mul_f32 v[98:99], v[98:99], v[166:167] op_sel_hi:[1,0]
	v_pk_mul_f32 v[96:97], v[96:97], v[166:167] op_sel_hi:[1,0]
	v_pk_mul_f32 v[106:107], v[106:107], v[166:167] op_sel_hi:[1,0]
	v_pk_mul_f32 v[104:105], v[104:105], v[166:167] op_sel_hi:[1,0]
	v_pk_mul_f32 v[114:115], v[114:115], v[166:167] op_sel_hi:[1,0]
	v_pk_mul_f32 v[112:113], v[112:113], v[166:167] op_sel_hi:[1,0]

.LBB0_555:
	s_mov_b32 s0, s91
	s_mov_b32 s64, 0
	s_waitcnt vmcnt(0)
	s_waitcnt lgkmcnt(0)
	v_or_b32_e32 v0, s0, v230
	v_cmp_eq_u32_e32 vcc, 0, v0
	s_barrier
	s_and_saveexec_b64 s[0:1], vcc
	s_mov_b32 s70, 0x10000
	s_cbranch_execz .LBB0_599
	v_writelane_b32 v2, s4, 1
	v_writelane_b32 v2, s5, 2
	v_writelane_b32 v2, s6, 3
	v_writelane_b32 v2, s7, 4
	v_readlane_b32 s4, v254, 45
	v_readlane_b32 s5, v254, 46
	s_getreg_b32 s6, hwreg(HW_REG_XCC_ID, 0, 4)
	s_nop 0
	v_mov_b32_e32 v0, 0x20010
	ds_read_b32 v3, v0
	ds_read_b32 v4, v0 offset:4
	ds_read_b32 v5, v0 offset:8
	s_and_b32 s6, s6, 15
	s_lshl_b32 s6, s6, 8
	v_mov_b32_e32 v13, 0x3400
	v_mov_b32_e32 v8, 1
	v_mov_b32_e32 v14, 0
	s_waitcnt lgkmcnt(0)
	s_add_u32 s4, s4, 0xee42000
	s_addc_u32 s5, s5, 0
	v_mov_b32_e32 v6, s6
	v_add_u32_e32 v7, 0x400, v6
	v_add_u32_e32 v6, 0x1400, v6
	buffer_inv sc1
	global_atomic_add v9, v6, v8, s[4:5] sc0
	v_add_u32_e32 v10, 1, v5
	v_mul_lo_u32 v11, v10, v3
	v_mul_lo_u32 v12, v10, v4
	s_waitcnt vmcnt(0)
	v_add_u32_e32 v9, 1, v9
	v_cmp_eq_u32_e32 vcc, v9, v11
	s_cbranch_vccz .Lhb_poll_4
	buffer_wbl2 sc1
	s_waitcnt vmcnt(0)
	global_atomic_add v13, v8, s[4:5]

.LBB0_760:
	s_mov_b32 s0, s91
	s_mov_b32 s70, 0
	s_waitcnt vmcnt(0)
	s_waitcnt lgkmcnt(0)
	v_or_b32_e32 v0, s0, v230
	v_cmp_eq_u32_e32 vcc, 0, v0
	s_barrier
	s_and_saveexec_b64 s[0:1], vcc
	s_cbranch_execz .LBB0_804
	v_writelane_b32 v2, s4, 1
	v_writelane_b32 v2, s5, 2
	v_writelane_b32 v2, s6, 3
	v_writelane_b32 v2, s7, 4
	v_readlane_b32 s4, v254, 45
	v_readlane_b32 s5, v254, 46
	s_getreg_b32 s6, hwreg(HW_REG_XCC_ID, 0, 4)
	s_nop 0
	v_mov_b32_e32 v0, 0x20010
	ds_read_b32 v3, v0
	ds_read_b32 v4, v0 offset:4
	ds_read_b32 v5, v0 offset:8
	s_and_b32 s6, s6, 15
	s_lshl_b32 s6, s6, 8
	v_mov_b32_e32 v13, 0x3400
	v_mov_b32_e32 v8, 1
	v_mov_b32_e32 v14, 0
	s_waitcnt lgkmcnt(0)
	s_add_u32 s4, s4, 0xee42000
	s_addc_u32 s5, s5, 0
	v_mov_b32_e32 v6, s6
	v_add_u32_e32 v7, 0x400, v6
	v_add_u32_e32 v6, 0x1400, v6
	buffer_inv sc1
	global_atomic_add v9, v6, v8, s[4:5] sc0
	v_add_u32_e32 v10, 1, v5
	v_mul_lo_u32 v11, v10, v3
	v_mul_lo_u32 v12, v10, v4
	s_waitcnt vmcnt(0)
	v_add_u32_e32 v9, 1, v9
	v_cmp_eq_u32_e32 vcc, v9, v11
	s_cbranch_vccz .Lhb_poll_5
	buffer_wbl2 sc1
	s_waitcnt vmcnt(0)
	global_atomic_add v13, v8, s[4:5]

.LBB0_1032:
	v_writelane_b32 v255, s82, 18
	s_nop 1
	v_writelane_b32 v255, s83, 19
	s_mov_b64 s[82:83], 0x20000
	s_or_b64 exec, exec, s[6:7]
	s_mov_b32 s0, s91
	s_mov_b32 s70, 0
	s_waitcnt vmcnt(0)
	s_waitcnt lgkmcnt(0)
	v_or_b32_e32 v0, s0, v230
	v_cmp_eq_u32_e32 vcc, 0, v0
	s_barrier
	s_and_saveexec_b64 s[0:1], vcc
	s_cbranch_execz .LBB0_1076
	v_writelane_b32 v2, s4, 1
	v_writelane_b32 v2, s5, 2
	v_writelane_b32 v2, s6, 3
	v_writelane_b32 v2, s7, 4
	v_readlane_b32 s4, v254, 45
	v_readlane_b32 s5, v254, 46
	s_getreg_b32 s6, hwreg(HW_REG_XCC_ID, 0, 4)
	s_nop 0
	v_mov_b32_e32 v0, 0x20010
	ds_read_b32 v3, v0
	ds_read_b32 v4, v0 offset:4
	ds_read_b32 v5, v0 offset:8
	s_and_b32 s6, s6, 15
	s_lshl_b32 s6, s6, 8
	v_mov_b32_e32 v13, 0x3400
	v_mov_b32_e32 v8, 1
	v_mov_b32_e32 v14, 0
	s_waitcnt lgkmcnt(0)
	s_add_u32 s4, s4, 0xee42000
	s_addc_u32 s5, s5, 0
	v_mov_b32_e32 v6, s6
	v_add_u32_e32 v7, 0x400, v6
	v_add_u32_e32 v6, 0x1400, v6
	buffer_inv sc1
	global_atomic_add v9, v6, v8, s[4:5] sc0
	v_add_u32_e32 v10, 1, v5
	v_mul_lo_u32 v11, v10, v3
	v_mul_lo_u32 v12, v10, v4
	s_waitcnt vmcnt(0)
	v_add_u32_e32 v9, 1, v9
	v_cmp_eq_u32_e32 vcc, v9, v11
	s_cbranch_vccz .Lhb_poll_7
	buffer_wbl2 sc1
	s_waitcnt vmcnt(0)
	global_atomic_add v13, v8, s[4:5]

.LBB0_1096:
	s_mov_b32 s0, s91
	s_mov_b32 s36, 0
	s_waitcnt vmcnt(0)
	s_waitcnt vmcnt(0) lgkmcnt(0)
	v_or_b32_e32 v0, s0, v230
	v_cmp_eq_u32_e32 vcc, 0, v0
	s_barrier
	s_and_saveexec_b64 s[0:1], vcc
	s_mov_b32 s70, 0x5a3e000
	s_cbranch_execz .LBB0_1140
	v_writelane_b32 v2, s4, 1
	v_writelane_b32 v2, s5, 2
	v_writelane_b32 v2, s6, 3
	v_writelane_b32 v2, s7, 4
	v_readlane_b32 s4, v254, 45
	v_readlane_b32 s5, v254, 46
	s_getreg_b32 s6, hwreg(HW_REG_XCC_ID, 0, 4)
	s_nop 0
	v_mov_b32_e32 v0, 0x20010
	ds_read_b32 v3, v0
	ds_read_b32 v4, v0 offset:4
	ds_read_b32 v5, v0 offset:8
	s_and_b32 s6, s6, 15
	s_lshl_b32 s6, s6, 8
	v_mov_b32_e32 v13, 0x3400
	v_mov_b32_e32 v8, 1
	v_mov_b32_e32 v14, 0
	s_waitcnt lgkmcnt(0)
	s_add_u32 s4, s4, 0xee42000
	s_addc_u32 s5, s5, 0
	v_mov_b32_e32 v6, s6
	v_add_u32_e32 v7, 0x400, v6
	v_add_u32_e32 v6, 0x1400, v6
	buffer_inv sc1
	global_atomic_add v9, v6, v8, s[4:5] sc0
	v_add_u32_e32 v10, 1, v5
	v_mul_lo_u32 v11, v10, v3
	v_mul_lo_u32 v12, v10, v4
	s_waitcnt vmcnt(0)
	v_add_u32_e32 v9, 1, v9
	v_cmp_eq_u32_e32 vcc, v9, v11
	s_cbranch_vccz .Lhb_poll_8
	buffer_wbl2 sc1
	s_waitcnt vmcnt(0)
	global_atomic_add v13, v8, s[4:5]

.LBB0_1146:
	v_mov_b32_e32 v0, v230
	s_mov_b32 s4, s91
	s_mov_b32 s65, s25
	s_mov_b32 s64, 0
	s_xor_b64 s[0:1], s[64:65], s[62:63]
	v_readlane_b32 s5, v253, 29
	s_add_u32 s0, s0, s5
	s_addc_u32 s1, s1, 0
	s_ashr_i32 s5, s4, 2
	s_andn2_b32 s5, s5, 63
	v_and_or_b32 v134, v0, 15, s5
	s_lshr_b32 s4, s4, 1
	v_readlane_b32 s5, v253, 46
	s_and_b32 s4, s4, 0x60
	v_ashrrev_i32_e32 v0, 1, v0
	v_add_u32_e32 v130, s5, v134
	v_readlane_b32 s5, v253, 38
	v_and_b32_e32 v0, -8, v0
	s_add_i32 s4, s4, s5
	v_add_u32_e32 v132, s4, v0
	v_readlane_b32 s4, v253, 40
	v_cvt_pk_bf16_f32 v110, v110, v111
	v_cvt_pk_bf16_f32 v111, v112, v113
	v_cvt_pk_bf16_f32 v112, v106, v107
	v_add_u32_e32 v106, s4, v134
	v_readlane_b32 s4, v253, 41
	v_cvt_pk_bf16_f32 v94, v94, v95
	v_cvt_pk_bf16_f32 v95, v96, v97
	v_cvt_pk_bf16_f32 v96, v90, v91
	v_add_u32_e32 v90, s4, v134
	v_readlane_b32 s4, v253, 42
	v_cvt_pk_bf16_f32 v78, v78, v79
	v_cvt_pk_bf16_f32 v79, v80, v81
	v_cvt_pk_bf16_f32 v80, v74, v75
	v_add_u32_e32 v74, s4, v134
	v_readlane_b32 s4, v253, 43
	v_cvt_pk_bf16_f32 v70, v70, v71
	v_cvt_pk_bf16_f32 v71, v72, v73
	v_cvt_pk_bf16_f32 v72, v66, v67
	v_add_u32_e32 v66, s4, v134
	v_ashrrev_i32_e32 v131, 31, v130
	v_ashrrev_i32_e32 v67, 31, v66
	v_readlane_b32 s4, v253, 44
	v_lshlrev_b64 v[130:131], 11, v[130:131]
	v_ashrrev_i32_e32 v133, 31, v132
	v_lshlrev_b64 v[66:67], 11, v[66:67]
	v_cvt_pk_bf16_f32 v46, v46, v47
	v_cvt_pk_bf16_f32 v47, v48, v49
	v_cvt_pk_bf16_f32 v48, v42, v43
	v_add_u32_e32 v42, s4, v134
	v_lshl_add_u64 v[130:131], s[0:1], 0, v[130:131]
	v_cvt_pk_bf16_f32 v126, v126, v127
	v_cvt_pk_bf16_f32 v127, v128, v129
	v_cvt_pk_bf16_f32 v128, v122, v123
	v_lshlrev_b64 v[122:123], 1, v[132:133]
	v_ashrrev_i32_e32 v107, 31, v106
	v_lshl_add_u64 v[66:67], s[0:1], 0, v[66:67]
	v_ashrrev_i32_e32 v43, 31, v42
	v_readlane_b32 s4, v253, 45
	v_cvt_pk_bf16_f32 v129, v124, v125
	v_lshl_add_u64 v[124:125], v[130:131], 0, v[122:123]
	v_cvt_pk_bf16_f32 v113, v108, v109
	v_lshlrev_b64 v[106:107], 11, v[106:107]
	v_cvt_pk_bf16_f32 v62, v62, v63
	v_cvt_pk_bf16_f32 v63, v64, v65
	v_cvt_pk_bf16_f32 v64, v58, v59
	v_lshl_add_u64 v[58:59], v[66:67], 0, v[122:123]
	v_cvt_pk_bf16_f32 v49, v44, v45
	v_lshlrev_b64 v[42:43], 11, v[42:43]
	v_cvt_pk_bf16_f32 v30, v30, v31
	v_cvt_pk_bf16_f32 v31, v32, v33
	v_cvt_pk_bf16_f32 v32, v26, v27
	v_add_u32_e32 v26, s4, v134
	flat_store_dwordx4 v[124:125], v[110:113] offset:256
	v_ashrrev_i32_e32 v91, 31, v90
	flat_store_dwordx4 v[58:59], v[46:49] offset:256
	v_lshl_add_u64 v[110:111], s[0:1], 0, v[106:107]
	v_ashrrev_i32_e32 v27, 31, v26
	v_lshl_add_u64 v[46:47], s[0:1], 0, v[42:43]
	v_readlane_b32 s4, v253, 47
	v_lshl_add_u64 v[110:111], v[110:111], 0, v[122:123]
	v_cvt_pk_bf16_f32 v97, v92, v93
	v_lshlrev_b64 v[90:91], 11, v[90:91]
	v_lshl_add_u64 v[46:47], v[46:47], 0, v[122:123]
	v_cvt_pk_bf16_f32 v33, v28, v29
	v_lshlrev_b64 v[26:27], 11, v[26:27]
	v_cvt_pk_bf16_f32 v14, v14, v15
	v_cvt_pk_bf16_f32 v15, v16, v17
	v_cvt_pk_bf16_f32 v16, v10, v11
	v_add_u32_e32 v10, s4, v134
	flat_store_dwordx4 v[110:111], v[94:97] offset:256
	v_ashrrev_i32_e32 v75, 31, v74
	flat_store_dwordx4 v[46:47], v[30:33] offset:256
	v_lshl_add_u64 v[94:95], s[0:1], 0, v[90:91]
	v_ashrrev_i32_e32 v11, 31, v10
	v_lshl_add_u64 v[30:31], s[0:1], 0, v[26:27]
	v_lshl_add_u64 v[94:95], v[94:95], 0, v[122:123]
	v_cvt_pk_bf16_f32 v81, v76, v77
	v_lshlrev_b64 v[74:75], 11, v[74:75]
	v_lshl_add_u64 v[30:31], v[30:31], 0, v[122:123]
	v_cvt_pk_bf16_f32 v17, v12, v13
	v_lshlrev_b64 v[10:11], 11, v[10:11]
	flat_store_dwordx4 v[94:95], v[78:81] offset:256
	flat_store_dwordx4 v[30:31], v[14:17] offset:256
	v_cvt_pk_bf16_f32 v106, v118, v119
	v_lshl_add_u64 v[78:79], s[0:1], 0, v[74:75]
	v_lshl_add_u64 v[14:15], s[0:1], 0, v[10:11]
	v_cvt_pk_bf16_f32 v107, v120, v121
	v_cvt_pk_bf16_f32 v108, v114, v115
	v_cvt_pk_bf16_f32 v109, v116, v117
	v_cvt_pk_bf16_f32 v90, v102, v103
	v_cvt_pk_bf16_f32 v91, v104, v105
	v_cvt_pk_bf16_f32 v92, v98, v99
	v_cvt_pk_bf16_f32 v93, v100, v101
	v_cvt_pk_bf16_f32 v74, v86, v87
	v_cvt_pk_bf16_f32 v75, v88, v89
	v_cvt_pk_bf16_f32 v76, v82, v83
	v_cvt_pk_bf16_f32 v77, v84, v85
	v_lshl_add_u64 v[78:79], v[78:79], 0, v[122:123]
	v_cvt_pk_bf16_f32 v73, v68, v69
	v_cvt_pk_bf16_f32 v65, v60, v61
	v_cvt_pk_bf16_f32 v42, v54, v55
	v_cvt_pk_bf16_f32 v43, v56, v57
	v_cvt_pk_bf16_f32 v44, v50, v51
	v_cvt_pk_bf16_f32 v45, v52, v53
	v_cvt_pk_bf16_f32 v26, v38, v39
	v_cvt_pk_bf16_f32 v27, v40, v41
	v_cvt_pk_bf16_f32 v28, v34, v35
	v_cvt_pk_bf16_f32 v29, v36, v37
	v_cvt_pk_bf16_f32 v10, v22, v23
	v_cvt_pk_bf16_f32 v11, v24, v25
	v_cvt_pk_bf16_f32 v12, v18, v19
	v_cvt_pk_bf16_f32 v13, v20, v21
	v_lshl_add_u64 v[14:15], v[14:15], 0, v[122:123]
	v_cvt_pk_bf16_f32 v6, v6, v7
	v_cvt_pk_bf16_f32 v7, v8, v9
	v_cvt_pk_bf16_f32 v8, v2, v3
	v_cvt_pk_bf16_f32 v9, v4, v5
	flat_store_dwordx4 v[124:125], v[126:129]
	flat_store_dwordx4 v[110:111], v[106:109]
	flat_store_dwordx4 v[94:95], v[90:93]
	flat_store_dwordx4 v[78:79], v[74:77]
	flat_store_dwordx4 v[78:79], v[70:73] offset:256
	flat_store_dwordx4 v[58:59], v[62:65]
	flat_store_dwordx4 v[46:47], v[42:45]
	flat_store_dwordx4 v[30:31], v[26:29]
	flat_store_dwordx4 v[14:15], v[10:13]
	flat_store_dwordx4 v[14:15], v[6:9] offset:256
	s_mov_b32 s0, s91
	s_waitcnt vmcnt(0)
	s_barrier
	s_mov_b32 s64, 0
	s_waitcnt vmcnt(0)
	s_waitcnt vmcnt(0) lgkmcnt(0)
	v_or_b32_e32 v0, s0, v230
	v_cmp_eq_u32_e32 vcc, 0, v0
	s_barrier
	s_and_saveexec_b64 s[0:1], vcc
	s_movk_i32 s66, 0x1e00
	s_mov_b32 s67, 0x800000
	s_cbranch_execz .LBB0_1190
	v_writelane_b32 v2, s4, 1
	v_writelane_b32 v2, s5, 2
	v_writelane_b32 v2, s6, 3
	v_writelane_b32 v2, s7, 4
	v_readlane_b32 s4, v254, 45
	v_readlane_b32 s5, v254, 46
	s_getreg_b32 s6, hwreg(HW_REG_XCC_ID, 0, 4)
	s_nop 0
	v_mov_b32_e32 v0, 0x20010
	ds_read_b32 v3, v0
	ds_read_b32 v4, v0 offset:4
	ds_read_b32 v5, v0 offset:8
	s_and_b32 s6, s6, 15
	s_lshl_b32 s6, s6, 8
	v_mov_b32_e32 v13, 0x3400
	v_mov_b32_e32 v8, 1
	v_mov_b32_e32 v14, 0
	s_waitcnt lgkmcnt(0)
	s_add_u32 s4, s4, 0xee42000
	s_addc_u32 s5, s5, 0
	v_mov_b32_e32 v6, s6
	v_add_u32_e32 v7, 0x400, v6
	v_add_u32_e32 v6, 0x1400, v6
	buffer_inv sc1
	global_atomic_add v9, v6, v8, s[4:5] sc0
	v_add_u32_e32 v10, 1, v5
	v_mul_lo_u32 v11, v10, v3
	v_mul_lo_u32 v12, v10, v4
	s_waitcnt vmcnt(0)
	v_add_u32_e32 v9, 1, v9
	v_cmp_eq_u32_e32 vcc, v9, v11
	s_cbranch_vccz .Lhb_poll_9
	buffer_wbl2 sc1
	s_waitcnt vmcnt(0)
	global_atomic_add v13, v8, s[4:5]

.LBB0_1212:
	v_writelane_b32 v2, s4, 1
	v_writelane_b32 v2, s5, 2
	v_writelane_b32 v2, s6, 3
	v_writelane_b32 v2, s7, 4
	v_readlane_b32 s4, v254, 45
	v_readlane_b32 s5, v254, 46
	s_getreg_b32 s6, hwreg(HW_REG_XCC_ID, 0, 4)
	s_nop 0
	v_mov_b32_e32 v0, 0x20010
	ds_read_b32 v3, v0
	ds_read_b32 v4, v0 offset:4
	ds_read_b32 v5, v0 offset:8
	s_and_b32 s6, s6, 15
	s_lshl_b32 s6, s6, 8
	v_mov_b32_e32 v13, 0x3400
	v_mov_b32_e32 v8, 1
	v_mov_b32_e32 v14, 0
	s_waitcnt lgkmcnt(0)
	s_add_u32 s4, s4, 0xee42000
	s_addc_u32 s5, s5, 0
	v_mov_b32_e32 v6, s6
	v_add_u32_e32 v7, 0x400, v6
	v_add_u32_e32 v6, 0x1400, v6
	buffer_inv sc1
	global_atomic_add v9, v6, v8, s[4:5] sc0
	v_add_u32_e32 v10, 1, v5
	v_mul_lo_u32 v11, v10, v3
	v_mul_lo_u32 v12, v10, v4
	s_waitcnt vmcnt(0)
	v_add_u32_e32 v9, 1, v9
	v_cmp_eq_u32_e32 vcc, v9, v11
	s_cbranch_vccz .Lhb_poll_10
	buffer_wbl2 sc1
	s_waitcnt vmcnt(0)
	global_atomic_add v13, v8, s[4:5]
